# up-proj: drop 30 redundant vmcnt/lgkmcnt waits after hoisted gain loads; ukv V slab flush batched (8 LDS reads, one wait, 8 global stores)
# baseline (speedup 1.0000x reference)
; #define SBAR() __builtin_amdgcn_sched_barrier(0)
; DEV void glds16(const u16* g, char* l) { __builtin_amdgcn_global_load_lds((const unsigned*)g, (unsigned*)l, 16, 0, 0); }
; #define GLOAD(kt, buf) do { _Pragma("unroll") for (int i = 0; i < 4; ++i) glds16(Ap + (long)i * 64 * lda + (kt) * 64, As + (buf) * 32768 + soff + i * 8192); \
;     _Pragma("unroll") for (int i = 0; i < NB; ++i) glds16(Bp + (long)i * 64 * ldb + (kt) * 64, Bs + (buf) * 32768 + soff + i * 8192); } while (0)
; template <int WM, int WN, int BN, int EPI>
; DEV void gemm_tile(const u16* __restrict__ A, int lda, const u16* __restrict__ Bt, int ldb, int K, int m0, char* lds,
;                    const Params& P, int layer, int batch, int nt) {
;     ...
;   const int srow = tid >> 3, sch = (tid & 7) ^ ((srow >> 1) & 7);
;   const u16* Ap = A + (long)(m0 + srow) * lda + sch * 8;
;   const u16* Bp = Bt + (long)srow * ldb + sch * 8;
;   const int soff = tid * 16;
;     ...
;   GLOAD(0, 0); asm volatile("s_waitcnt vmcnt(0)" ::: "memory"); __syncthreads();
;   const int nk = K >> 6;
;   for (int kt = 0; kt < nk; ++kt) {
;     const bool more = kt + 1 < nk;
;     const int nb = (kt + 1) & 1;
;     const char* as = As + (kt & 1) * 32768; const char* bs = Bs + (kt & 1) * 32768;
; #pragma unroll
;     for (int ks = 0; ks < 4; ++ks) {
;       if (more) { glds16(Ap + (long)ks * 64 * lda + (kt + 1) * 64, As + nb * 32768 + soff + ks * 8192);
;                   if (ks < NB) glds16(Bp + (long)ks * 64 * ldb + (kt + 1) * 64, Bs + nb * 32768 + soff + ks * 8192); }
;       SBAR();
;       bf16x8 xf[MI], wf[NI];
; #pragma unroll
;       for (int mi = 0; mi < MI; ++mi) xf[mi] = *reinterpret_cast<const bf16x8*>(as + swz128(wm * (MI * 32) + mi * 32 + r32, ks * 2 + hi));
; #pragma unroll
;       for (int ni = 0; ni < NI; ++ni) wf[ni] = *reinterpret_cast<const bf16x8*>(bs + swz128(wn * (NI * 32) + ni * 32 + r32, ks * 2 + hi));
; #pragma unroll
;       for (int mi = 0; mi < MI; ++mi)
; #pragma unroll
;         for (int ni = 0; ni < NI; ++ni) acc[mi][ni] = __builtin_amdgcn_mfma_f32_32x32x16_bf16(wf[ni], xf[mi], acc[mi][ni], 0, 0, 0);
;     }
;     asm volatile("s_waitcnt vmcnt(0)" ::: "memory");
;     __syncthreads();
;   }
.LBB0_358:
	s_mul_i32 s2, s54, 0xc0
	s_mul_i32 s3, s51, 0x300
	s_add_i32 s3, s2, s3
	s_lshl_b32 s3, s3, 9
	s_add_u32 s60, s36, s3
	s_addc_u32 s61, s38, 0
	s_lshl_b32 s3, s55, 8
	v_mov_b32_e32 v100, v226
	s_and_b32 s3, s3, 0x3f00
	s_add_i32 s22, 0, 0x10000
	v_ashrrev_i32_e32 v0, 3, v100
	v_lshrrev_b32_e32 v1, 4, v100
	v_add_u32_e32 v2, s3, v0
	v_xor_b32_e32 v1, v1, v100
	v_ashrrev_i32_e32 v3, 31, v2
	v_lshlrev_b32_e32 v5, 4, v100
	v_lshlrev_b64 v[2:3], 9, v[2:3]
	v_lshlrev_b32_e32 v1, 4, v1
	v_add_u32_e32 v120, 0, v5
	v_lshl_add_u64 v[2:3], s[6:7], 0, v[2:3]
	v_and_b32_e32 v184, 0x70, v1
	v_readfirstlane_b32 s82, v120
	v_add_u32_e32 v6, 0x2000, v120
	v_lshl_add_u64 v[96:97], v[2:3], 0, v[184:185]
	v_ashrrev_i32_e32 v1, 31, v0
	s_mov_b32 m0, s82
	v_readfirstlane_b32 s79, v6
	v_add_u32_e32 v6, 0x4000, v120
	v_lshlrev_b64 v[0:1], 9, v[0:1]
	global_load_lds_dwordx4 v[96:97], off
	v_lshl_add_u64 v[2:3], v[96:97], 0, s[40:41]
	s_mov_b32 m0, s79
	v_readfirstlane_b32 s65, v6
	v_lshl_add_u64 v[0:1], s[60:61], 0, v[0:1]
	global_load_lds_dwordx4 v[2:3], off
	v_lshl_add_u64 v[2:3], v[96:97], 0, s[28:29]
	s_mov_b32 m0, s65
	s_mov_b64 s[60:61], 0x18000
	v_add_u32_e32 v6, 0x6000, v120
	global_load_lds_dwordx4 v[2:3], off
	v_lshl_add_u64 v[2:3], v[96:97], 0, s[60:61]
	v_readfirstlane_b32 s60, v6
	s_mov_b32 m0, s60
	v_add_u32_e32 v121, s22, v5
	global_load_lds_dwordx4 v[2:3], off
	v_readfirstlane_b32 s81, v121
	v_add_u32_e32 v2, 0x2000, v121
	v_lshl_add_u64 v[98:99], v[0:1], 0, v[184:185]
	s_mov_b32 m0, s81
	v_readfirstlane_b32 s75, v2
	v_add_u32_e32 v2, 0x4000, v121
	global_load_lds_dwordx4 v[98:99], off
	v_lshl_add_u64 v[0:1], v[98:99], 0, s[40:41]
	s_mov_b32 m0, s75
	v_readfirstlane_b32 s61, v2
	v_and_b32_e32 v101, 31, v100
	global_load_lds_dwordx4 v[0:1], off
	v_lshl_add_u64 v[0:1], v[98:99], 0, s[28:29]
	s_mov_b32 m0, s61
	v_add_u32_e32 v5, 0x8000, v120
	v_ashrrev_i32_e32 v103, 6, v100
	global_load_lds_dwordx4 v[0:1], off
	v_lshlrev_b32_e32 v1, 7, v101
	v_add_u32_e32 v6, 0x8000, v121
	v_readfirstlane_b32 s62, v5
	v_lshlrev_b32_e32 v0, 12, v103
	v_add_u32_e32 v124, s22, v1
	v_lshl_add_u64 v[2:3], v[96:97], 0, s[30:31]
	s_mov_b32 m0, s62
	v_readfirstlane_b32 s22, v6
	s_waitcnt vmcnt(0)
	s_waitcnt vmcnt(0) lgkmcnt(0)
	s_barrier
	v_add3_u32 v123, 0, v0, v1
	v_lshl_add_u64 v[0:1], v[98:99], 0, s[30:31]
	global_load_lds_dwordx4 v[2:3], off
	s_mov_b32 m0, s22
	v_lshrrev_b32_e32 v4, 5, v100
	global_load_lds_dwordx4 v[0:1], off
	v_bfe_u32 v102, v100, 5, 1
	v_bfe_u32 v122, v100, 1, 3
	v_bitop3_b32 v0, v4, v122, 1 bitop3:0x6c
	v_lshlrev_b32_e32 v4, 4, v0
	v_add_u32_e32 v104, v124, v4
	ds_read_b128 v[0:3], v104
	v_add_u32_e32 v125, v123, v4
	ds_read_b128 v[16:19], v125
	v_add_u32_e32 v26, 0xa000, v121
	v_lshl_add_u64 v[24:25], v[96:97], 0, s[42:43]
	v_readfirstlane_b32 s63, v26
	s_waitcnt lgkmcnt(0)
	v_mfma_f32_32x32x16_bf16 v[80:95], v[0:3], v[16:19], 0
	ds_read_b128 v[0:3], v104 offset:4096
	ds_read_b128 v[4:7], v104 offset:8192
	s_waitcnt lgkmcnt(0)
	v_mfma_f32_32x32x16_bf16 v[64:79], v[0:3], v[16:19], 0
	v_mfma_f32_32x32x16_bf16 v[48:63], v[4:7], v[16:19], 0
	ds_read_b128 v[0:3], v104 offset:12288
	ds_read_b128 v[4:7], v104 offset:16384
	ds_read_b128 v[20:23], v104 offset:20480
	s_waitcnt lgkmcnt(0)
	v_mfma_f32_32x32x16_bf16 v[32:47], v[0:3], v[16:19], 0
	v_add_u32_e32 v0, 0xa000, v120
	s_nop 0
	v_readfirstlane_b32 s74, v0
	s_mov_b32 m0, s74
	s_nop 0
	global_load_lds_dwordx4 v[24:25], off
	v_lshl_add_u64 v[24:25], v[98:99], 0, s[42:43]
	s_mov_b32 m0, s63
	v_mfma_f32_32x32x16_bf16 v[0:15], v[4:7], v[16:19], 0
	global_load_lds_dwordx4 v[24:25], off
	v_mfma_f32_32x32x16_bf16 v[16:31], v[20:23], v[16:19], 0
	v_bitop3_b32 v105, v102, v122, 2 bitop3:0x36
	v_lshlrev_b32_e32 v110, 4, v105
	v_add_u32_e32 v105, v124, v110
	ds_read_b128 v[106:109], v105
	v_add_u32_e32 v126, v123, v110
	ds_read_b128 v[110:113], v126
	v_add_u32_e32 v127, 0xc000, v120
	s_mov_b64 s[86:87], 0x10080
	v_readfirstlane_b32 s78, v127
	v_lshl_add_u64 v[118:119], v[96:97], 0, s[86:87]
	s_mov_b32 m0, s78
	s_waitcnt lgkmcnt(0)
	v_mfma_f32_32x32x16_bf16 v[80:95], v[106:109], v[110:113], v[80:95]
	ds_read_b128 v[106:109], v105 offset:4096
	ds_read_b128 v[114:117], v105 offset:8192
	s_waitcnt lgkmcnt(0)
	v_mfma_f32_32x32x16_bf16 v[64:79], v[106:109], v[110:113], v[64:79]
	v_mfma_f32_32x32x16_bf16 v[48:63], v[114:117], v[110:113], v[48:63]
	ds_read_b128 v[106:109], v105 offset:12288
	ds_read_b128 v[114:117], v105 offset:16384
	s_waitcnt lgkmcnt(0)
	v_mfma_f32_32x32x16_bf16 v[0:15], v[114:117], v[110:113], v[0:15]
	v_add_u32_e32 v116, 0xc000, v121
	v_lshl_add_u64 v[114:115], v[98:99], 0, s[86:87]
	v_readfirstlane_b32 s64, v116
	v_mfma_f32_32x32x16_bf16 v[32:47], v[106:109], v[110:113], v[32:47]
	ds_read_b128 v[106:109], v105 offset:20480
	global_load_lds_dwordx4 v[118:119], off
	s_mov_b32 m0, s64
	s_nop 0
	global_load_lds_dwordx4 v[114:115], off
	s_waitcnt lgkmcnt(0)
	v_mfma_f32_32x32x16_bf16 v[16:31], v[106:109], v[110:113], v[16:31]
	v_bitop3_b32 v106, v102, v122, 4 bitop3:0x36
	v_lshlrev_b32_e32 v110, 4, v106
	v_add_u32_e32 v118, v124, v110
	ds_read_b128 v[106:109], v118
	v_add_u32_e32 v119, v123, v110
	ds_read_b128 v[110:113], v119
	s_mov_b64 s[86:87], 0x18080
	s_waitcnt lgkmcnt(0)
	v_mfma_f32_32x32x16_bf16 v[80:95], v[106:109], v[110:113], v[80:95]
	ds_read_b128 v[106:109], v118 offset:4096
	ds_read_b128 v[114:117], v118 offset:8192
	s_waitcnt lgkmcnt(0)
	v_mfma_f32_32x32x16_bf16 v[64:79], v[106:109], v[110:113], v[64:79]
	v_mfma_f32_32x32x16_bf16 v[48:63], v[114:117], v[110:113], v[48:63]
	ds_read_b128 v[106:109], v118 offset:12288
	ds_read_b128 v[114:117], v118 offset:16384
	s_waitcnt lgkmcnt(0)
; #define SBAR() __builtin_amdgcn_sched_barrier(0)
; DEV void glds16(const u16* g, char* l) { __builtin_amdgcn_global_load_lds((const unsigned*)g, (unsigned*)l, 16, 0, 0); }
; template <int WM, int WN, int BN, int EPI>
; DEV void gemm_tile(const u16* __restrict__ A, int lda, const u16* __restrict__ Bt, int ldb, int K, int m0, char* lds,
;                    const Params& P, int layer, int batch, int nt) {
;     ...
;   for (int kt = 0; kt < nk; ++kt) {
;     const bool more = kt + 1 < nk;
;     const int nb = (kt + 1) & 1;
;     const char* as = As + (kt & 1) * 32768; const char* bs = Bs + (kt & 1) * 32768;
; #pragma unroll
;     for (int ks = 0; ks < 4; ++ks) {
;       if (more) { glds16(Ap + (long)ks * 64 * lda + (kt + 1) * 64, As + nb * 32768 + soff + ks * 8192);
;                   if (ks < NB) glds16(Bp + (long)ks * 64 * ldb + (kt + 1) * 64, Bs + nb * 32768 + soff + ks * 8192); }
;       SBAR();
;       bf16x8 xf[MI], wf[NI];
; #pragma unroll
;       for (int mi = 0; mi < MI; ++mi) xf[mi] = *reinterpret_cast<const bf16x8*>(as + swz128(wm * (MI * 32) + mi * 32 + r32, ks * 2 + hi));
; #pragma unroll
;       for (int ni = 0; ni < NI; ++ni) wf[ni] = *reinterpret_cast<const bf16x8*>(bs + swz128(wn * (NI * 32) + ni * 32 + r32, ks * 2 + hi));
; #pragma unroll
;       for (int mi = 0; mi < MI; ++mi)
; #pragma unroll
;         for (int ni = 0; ni < NI; ++ni) acc[mi][ni] = __builtin_amdgcn_mfma_f32_32x32x16_bf16(wf[ni], xf[mi], acc[mi][ni], 0, 0, 0);
;     }
;     asm volatile("s_waitcnt vmcnt(0)" ::: "memory");
;     __syncthreads();
;   }
	v_mfma_f32_32x32x16_bf16 v[0:15], v[114:117], v[110:113], v[0:15]
	v_add_u32_e32 v116, 0xe000, v120
	v_lshl_add_u64 v[114:115], v[96:97], 0, s[86:87]
	v_readfirstlane_b32 s80, v116
	s_mov_b32 m0, s80
	v_mfma_f32_32x32x16_bf16 v[32:47], v[106:109], v[110:113], v[32:47]
	ds_read_b128 v[106:109], v118 offset:20480
	global_load_lds_dwordx4 v[114:115], off
	s_waitcnt lgkmcnt(0)
	v_mfma_f32_32x32x16_bf16 v[16:31], v[106:109], v[110:113], v[16:31]
	v_bitop3_b32 v106, v102, v122, 6 bitop3:0x36
	v_lshlrev_b32_e32 v110, 4, v106
	v_add_u32_e32 v124, v124, v110
	ds_read_b128 v[106:109], v124
	v_add_u32_e32 v120, v123, v110
	ds_read_b128 v[110:113], v120
	s_mov_b32 m0, s82
	s_mov_b64 s[82:83], 0x100
	s_waitcnt lgkmcnt(0)
	v_mfma_f32_32x32x16_bf16 v[80:95], v[106:109], v[110:113], v[80:95]
	ds_read_b128 v[106:109], v124 offset:4096
	ds_read_b128 v[114:117], v124 offset:8192
	s_waitcnt lgkmcnt(0)
	v_mfma_f32_32x32x16_bf16 v[64:79], v[106:109], v[110:113], v[64:79]
	v_mfma_f32_32x32x16_bf16 v[48:63], v[114:117], v[110:113], v[48:63]
	ds_read_b128 v[106:109], v124 offset:12288
	ds_read_b128 v[114:117], v124 offset:16384
	s_waitcnt lgkmcnt(0)
	v_mfma_f32_32x32x16_bf16 v[0:15], v[114:117], v[110:113], v[0:15]
	v_lshl_add_u64 v[116:117], v[96:97], 0, s[82:83]
	v_lshl_add_u64 v[114:115], v[98:99], 0, s[82:83]
	v_mfma_f32_32x32x16_bf16 v[32:47], v[106:109], v[110:113], v[32:47]
	ds_read_b128 v[106:109], v124 offset:20480
	s_waitcnt vmcnt(0)
	s_waitcnt vmcnt(0) lgkmcnt(0)
	s_barrier
	global_load_lds_dwordx4 v[116:117], off
	s_mov_b32 m0, s81
	v_mfma_f32_32x32x16_bf16 v[16:31], v[106:109], v[110:113], v[16:31]
	global_load_lds_dwordx4 v[114:115], off
	ds_read_b128 v[106:109], v104 offset:32768
	ds_read_b128 v[110:113], v125 offset:32768
	s_mov_b64 s[82:83], 0x8100
	s_mov_b32 m0, s79
	s_waitcnt lgkmcnt(0)
	v_mfma_f32_32x32x16_bf16 v[80:95], v[106:109], v[110:113], v[80:95]
	ds_read_b128 v[106:109], v104 offset:36864
	ds_read_b128 v[114:117], v104 offset:40960
	s_waitcnt lgkmcnt(0)
	v_mfma_f32_32x32x16_bf16 v[64:79], v[106:109], v[110:113], v[64:79]
	v_mfma_f32_32x32x16_bf16 v[48:63], v[114:117], v[110:113], v[48:63]
	ds_read_b128 v[106:109], v104 offset:45056
	ds_read_b128 v[114:117], v104 offset:49152
	s_waitcnt lgkmcnt(0)
	v_mfma_f32_32x32x16_bf16 v[0:15], v[114:117], v[110:113], v[0:15]
	v_lshl_add_u64 v[114:115], v[96:97], 0, s[82:83]
	v_mfma_f32_32x32x16_bf16 v[32:47], v[106:109], v[110:113], v[32:47]
	ds_read_b128 v[106:109], v104 offset:53248
	global_load_lds_dwordx4 v[114:115], off
	v_lshl_add_u64 v[114:115], v[98:99], 0, s[82:83]
	s_mov_b32 m0, s75
	s_nop 0
	global_load_lds_dwordx4 v[114:115], off
	s_waitcnt lgkmcnt(0)
	v_mfma_f32_32x32x16_bf16 v[16:31], v[106:109], v[110:113], v[16:31]
	ds_read_b128 v[106:109], v105 offset:32768
	ds_read_b128 v[110:113], v126 offset:32768
	s_mov_b64 s[82:83], 0x10100
	s_mov_b32 m0, s65
	s_waitcnt lgkmcnt(0)
	v_mfma_f32_32x32x16_bf16 v[80:95], v[106:109], v[110:113], v[80:95]
	ds_read_b128 v[106:109], v105 offset:36864
	ds_read_b128 v[114:117], v105 offset:40960
	s_waitcnt lgkmcnt(0)
	v_mfma_f32_32x32x16_bf16 v[64:79], v[106:109], v[110:113], v[64:79]
	v_mfma_f32_32x32x16_bf16 v[48:63], v[114:117], v[110:113], v[48:63]
	ds_read_b128 v[106:109], v105 offset:45056
	ds_read_b128 v[114:117], v105 offset:49152
	s_waitcnt lgkmcnt(0)
	v_mfma_f32_32x32x16_bf16 v[0:15], v[114:117], v[110:113], v[0:15]
	v_lshl_add_u64 v[114:115], v[96:97], 0, s[82:83]
	v_mfma_f32_32x32x16_bf16 v[32:47], v[106:109], v[110:113], v[32:47]
	ds_read_b128 v[106:109], v105 offset:53248
	global_load_lds_dwordx4 v[114:115], off
	v_lshl_add_u64 v[114:115], v[98:99], 0, s[82:83]
	s_mov_b32 m0, s61
	s_nop 0
	global_load_lds_dwordx4 v[114:115], off
	s_waitcnt lgkmcnt(0)
	v_mfma_f32_32x32x16_bf16 v[16:31], v[106:109], v[110:113], v[16:31]
	ds_read_b128 v[106:109], v118 offset:32768
	ds_read_b128 v[110:113], v119 offset:32768
	s_mov_b32 m0, s60
	s_mov_b64 s[60:61], 0x18100
	s_waitcnt lgkmcnt(0)
	v_mfma_f32_32x32x16_bf16 v[80:95], v[106:109], v[110:113], v[80:95]
	ds_read_b128 v[106:109], v118 offset:36864
	ds_read_b128 v[114:117], v118 offset:40960
	s_waitcnt lgkmcnt(0)
	v_mfma_f32_32x32x16_bf16 v[64:79], v[106:109], v[110:113], v[64:79]
	v_mfma_f32_32x32x16_bf16 v[48:63], v[114:117], v[110:113], v[48:63]
	ds_read_b128 v[106:109], v118 offset:45056
	ds_read_b128 v[114:117], v118 offset:49152
	s_waitcnt lgkmcnt(0)
	v_mfma_f32_32x32x16_bf16 v[0:15], v[114:117], v[110:113], v[0:15]
	v_lshl_add_u64 v[114:115], v[96:97], 0, s[60:61]
	v_mfma_f32_32x32x16_bf16 v[32:47], v[106:109], v[110:113], v[32:47]
	ds_read_b128 v[106:109], v118 offset:53248
	global_load_lds_dwordx4 v[114:115], off
	s_waitcnt lgkmcnt(0)
	v_mfma_f32_32x32x16_bf16 v[16:31], v[106:109], v[110:113], v[16:31]
	ds_read_b128 v[106:109], v124 offset:32768
	ds_read_b128 v[110:113], v120 offset:32768
	s_mov_b64 s[60:61], 0x180
	s_mov_b32 m0, s62
	s_waitcnt lgkmcnt(0)
	v_mfma_f32_32x32x16_bf16 v[80:95], v[106:109], v[110:113], v[80:95]
	ds_read_b128 v[106:109], v124 offset:36864
	ds_read_b128 v[114:117], v124 offset:40960
	s_waitcnt lgkmcnt(0)
	v_mfma_f32_32x32x16_bf16 v[64:79], v[106:109], v[110:113], v[64:79]
	v_mfma_f32_32x32x16_bf16 v[48:63], v[114:117], v[110:113], v[48:63]
	ds_read_b128 v[106:109], v124 offset:45056
	ds_read_b128 v[114:117], v124 offset:49152
	s_waitcnt lgkmcnt(0)
	v_mfma_f32_32x32x16_bf16 v[0:15], v[114:117], v[110:113], v[0:15]
	v_lshl_add_u64 v[116:117], v[96:97], 0, s[60:61]
	v_lshl_add_u64 v[114:115], v[98:99], 0, s[60:61]
	v_mfma_f32_32x32x16_bf16 v[32:47], v[106:109], v[110:113], v[32:47]
	ds_read_b128 v[106:109], v124 offset:53248
	s_waitcnt vmcnt(0)
	s_waitcnt vmcnt(0) lgkmcnt(0)
	s_barrier
; #define SBAR() __builtin_amdgcn_sched_barrier(0)
; DEV void glds16(const u16* g, char* l) { __builtin_amdgcn_global_load_lds((const unsigned*)g, (unsigned*)l, 16, 0, 0); }
; DEV void epi_uq(f32x16 (&acc)[1][6], const Params& P, int layer, int batch, int m0, int head, int wid, int r32, int hi, char* lds) {
;   const int t = m0 + wid * 32 + r32;
;   const float rc = __builtin_amdgcn_rsqf((WS{P.ws}.ssq_cq()[t] + WS{P.ws}.ssq_cq()[TB + t] + WS{P.ws}.ssq_cq()[2 * TB + t] + WS{P.ws}.ssq_cq()[3 * TB + t]) * (1.f / 256.f) + EPS);
; template <int WM, int WN, int BN, int EPI>
; DEV void gemm_tile(const u16* __restrict__ A, int lda, const u16* __restrict__ Bt, int ldb, int K, int m0, char* lds,
;                    const Params& P, int layer, int batch, int nt) {
;     ...
;   for (int kt = 0; kt < nk; ++kt) {
;     const bool more = kt + 1 < nk;
;     const int nb = (kt + 1) & 1;
;     const char* as = As + (kt & 1) * 32768; const char* bs = Bs + (kt & 1) * 32768;
; #pragma unroll
;     for (int ks = 0; ks < 4; ++ks) {
;       if (more) { glds16(Ap + (long)ks * 64 * lda + (kt + 1) * 64, As + nb * 32768 + soff + ks * 8192);
;                   if (ks < NB) glds16(Bp + (long)ks * 64 * ldb + (kt + 1) * 64, Bs + nb * 32768 + soff + ks * 8192); }
;       SBAR();
;       bf16x8 xf[MI], wf[NI];
; #pragma unroll
;       for (int mi = 0; mi < MI; ++mi) xf[mi] = *reinterpret_cast<const bf16x8*>(as + swz128(wm * (MI * 32) + mi * 32 + r32, ks * 2 + hi));
; #pragma unroll
;       for (int ni = 0; ni < NI; ++ni) wf[ni] = *reinterpret_cast<const bf16x8*>(bs + swz128(wn * (NI * 32) + ni * 32 + r32, ks * 2 + hi));
; #pragma unroll
;       for (int mi = 0; mi < MI; ++mi)
; #pragma unroll
;         for (int ni = 0; ni < NI; ++ni) acc[mi][ni] = __builtin_amdgcn_mfma_f32_32x32x16_bf16(wf[ni], xf[mi], acc[mi][ni], 0, 0, 0);
;     }
;     asm volatile("s_waitcnt vmcnt(0)" ::: "memory");
;     __syncthreads();
;   }
	global_load_lds_dwordx4 v[116:117], off
	s_mov_b32 m0, s22
	v_mfma_f32_32x32x16_bf16 v[16:31], v[106:109], v[110:113], v[16:31]
	global_load_lds_dwordx4 v[114:115], off
	ds_read_b128 v[106:109], v104
	ds_read_b128 v[110:113], v125
	s_mov_b64 s[60:61], 0x8180
	s_mov_b32 m0, s74
	s_waitcnt lgkmcnt(0)
	v_mfma_f32_32x32x16_bf16 v[80:95], v[106:109], v[110:113], v[80:95]
	ds_read_b128 v[106:109], v104 offset:4096
	ds_read_b128 v[114:117], v104 offset:8192
	s_waitcnt lgkmcnt(0)
	v_mfma_f32_32x32x16_bf16 v[64:79], v[106:109], v[110:113], v[64:79]
	v_mfma_f32_32x32x16_bf16 v[48:63], v[114:117], v[110:113], v[48:63]
	ds_read_b128 v[106:109], v104 offset:12288
	ds_read_b128 v[114:117], v104 offset:16384
	s_waitcnt lgkmcnt(0)
	v_mfma_f32_32x32x16_bf16 v[0:15], v[114:117], v[110:113], v[0:15]
	v_lshl_add_u64 v[114:115], v[96:97], 0, s[60:61]
	v_mfma_f32_32x32x16_bf16 v[32:47], v[106:109], v[110:113], v[32:47]
	ds_read_b128 v[106:109], v104 offset:20480
	global_load_lds_dwordx4 v[114:115], off
	v_lshl_add_u64 v[114:115], v[98:99], 0, s[60:61]
	s_mov_b32 m0, s63
	s_nop 0
	global_load_lds_dwordx4 v[114:115], off
	s_waitcnt lgkmcnt(0)
	v_mfma_f32_32x32x16_bf16 v[16:31], v[106:109], v[110:113], v[16:31]
	ds_read_b128 v[106:109], v105
	ds_read_b128 v[110:113], v126
	s_mov_b64 s[60:61], 0x10180
	s_mov_b32 m0, s78
	v_lshl_add_u64 v[98:99], v[98:99], 0, s[60:61]
	s_waitcnt lgkmcnt(0)
	v_mfma_f32_32x32x16_bf16 v[80:95], v[106:109], v[110:113], v[80:95]
	ds_read_b128 v[106:109], v105 offset:4096
	ds_read_b128 v[114:117], v105 offset:8192
	s_waitcnt lgkmcnt(0)
	v_mfma_f32_32x32x16_bf16 v[64:79], v[106:109], v[110:113], v[64:79]
	v_mfma_f32_32x32x16_bf16 v[48:63], v[114:117], v[110:113], v[48:63]
	ds_read_b128 v[106:109], v105 offset:12288
	ds_read_b128 v[114:117], v105 offset:16384
	s_waitcnt lgkmcnt(0)
	v_mfma_f32_32x32x16_bf16 v[0:15], v[114:117], v[110:113], v[0:15]
	v_lshl_add_u64 v[114:115], v[96:97], 0, s[60:61]
	v_mfma_f32_32x32x16_bf16 v[32:47], v[106:109], v[110:113], v[32:47]
	ds_read_b128 v[106:109], v105 offset:20480
	global_load_lds_dwordx4 v[114:115], off
	s_mov_b32 m0, s64
	s_nop 0
	global_load_lds_dwordx4 v[98:99], off
	s_waitcnt lgkmcnt(0)
	v_mfma_f32_32x32x16_bf16 v[16:31], v[106:109], v[110:113], v[16:31]
	ds_read_b128 v[106:109], v118
	ds_read_b128 v[110:113], v119
	s_mov_b64 s[60:61], 0x18180
	s_mov_b32 m0, s80
	v_lshl_add_u64 v[96:97], v[96:97], 0, s[60:61]
	s_waitcnt lgkmcnt(0)
	v_mfma_f32_32x32x16_bf16 v[80:95], v[106:109], v[110:113], v[80:95]
	ds_read_b128 v[106:109], v118 offset:4096
	ds_read_b128 v[114:117], v118 offset:8192
	s_waitcnt lgkmcnt(0)
	v_mfma_f32_32x32x16_bf16 v[64:79], v[106:109], v[110:113], v[64:79]
	v_mfma_f32_32x32x16_bf16 v[48:63], v[114:117], v[110:113], v[48:63]
	ds_read_b128 v[106:109], v118 offset:12288
	ds_read_b128 v[114:117], v118 offset:16384
	s_waitcnt lgkmcnt(0)
	v_mfma_f32_32x32x16_bf16 v[32:47], v[106:109], v[110:113], v[32:47]
	ds_read_b128 v[106:109], v118 offset:20480
	global_load_lds_dwordx4 v[96:97], off
	v_mfma_f32_32x32x16_bf16 v[0:15], v[114:117], v[110:113], v[0:15]
	s_waitcnt lgkmcnt(0)
	v_mfma_f32_32x32x16_bf16 v[16:31], v[106:109], v[110:113], v[16:31]
	ds_read_b128 v[96:99], v124
	ds_read_b128 v[106:109], v120
	s_waitcnt lgkmcnt(0)
	v_mfma_f32_32x32x16_bf16 v[80:95], v[96:99], v[106:109], v[80:95]
	ds_read_b128 v[96:99], v124 offset:4096
	s_waitcnt lgkmcnt(0)
	v_mfma_f32_32x32x16_bf16 v[64:79], v[96:99], v[106:109], v[64:79]
	ds_read_b128 v[96:99], v124 offset:8192
	s_waitcnt lgkmcnt(0)
	v_mfma_f32_32x32x16_bf16 v[48:63], v[96:99], v[106:109], v[48:63]
	ds_read_b128 v[96:99], v124 offset:12288
	s_waitcnt lgkmcnt(0)
	v_mfma_f32_32x32x16_bf16 v[32:47], v[96:99], v[106:109], v[32:47]
	ds_read_b128 v[96:99], v124 offset:16384
	s_waitcnt lgkmcnt(0)
	v_mfma_f32_32x32x16_bf16 v[0:15], v[96:99], v[106:109], v[0:15]
	ds_read_b128 v[96:99], v124 offset:20480
	s_waitcnt vmcnt(0)
	s_waitcnt vmcnt(0) lgkmcnt(0)
	s_barrier
	v_mfma_f32_32x32x16_bf16 v[16:31], v[96:99], v[106:109], v[16:31]
	ds_read_b128 v[96:99], v104 offset:32768
	ds_read_b128 v[106:109], v125 offset:32768
	s_waitcnt lgkmcnt(0)
	v_mfma_f32_32x32x16_bf16 v[80:95], v[96:99], v[106:109], v[80:95]
	ds_read_b128 v[96:99], v104 offset:36864
	s_waitcnt lgkmcnt(0)
	v_mfma_f32_32x32x16_bf16 v[64:79], v[96:99], v[106:109], v[64:79]
	ds_read_b128 v[96:99], v104 offset:40960
	s_waitcnt lgkmcnt(0)
	v_mfma_f32_32x32x16_bf16 v[48:63], v[96:99], v[106:109], v[48:63]
	ds_read_b128 v[96:99], v104 offset:45056
	s_waitcnt lgkmcnt(0)
	v_mfma_f32_32x32x16_bf16 v[32:47], v[96:99], v[106:109], v[32:47]
	ds_read_b128 v[96:99], v104 offset:49152
	s_waitcnt lgkmcnt(0)
	v_mfma_f32_32x32x16_bf16 v[0:15], v[96:99], v[106:109], v[0:15]
	ds_read_b128 v[96:99], v104 offset:53248
	s_waitcnt lgkmcnt(0)
	v_mfma_f32_32x32x16_bf16 v[16:31], v[96:99], v[106:109], v[16:31]
	ds_read_b128 v[96:99], v105 offset:32768
	ds_read_b128 v[106:109], v126 offset:32768
	s_waitcnt lgkmcnt(0)
	v_mfma_f32_32x32x16_bf16 v[80:95], v[96:99], v[106:109], v[80:95]
	ds_read_b128 v[96:99], v105 offset:36864
	s_waitcnt lgkmcnt(0)
	v_mfma_f32_32x32x16_bf16 v[64:79], v[96:99], v[106:109], v[64:79]
	ds_read_b128 v[96:99], v105 offset:40960
	s_waitcnt lgkmcnt(0)
	v_mfma_f32_32x32x16_bf16 v[48:63], v[96:99], v[106:109], v[48:63]
	ds_read_b128 v[96:99], v105 offset:45056
	s_waitcnt lgkmcnt(0)
	v_mfma_f32_32x32x16_bf16 v[32:47], v[96:99], v[106:109], v[32:47]
	ds_read_b128 v[96:99], v105 offset:49152
	s_waitcnt lgkmcnt(0)
	v_mfma_f32_32x32x16_bf16 v[0:15], v[96:99], v[106:109], v[0:15]
	ds_read_b128 v[96:99], v105 offset:53248
	s_waitcnt lgkmcnt(0)
	v_mfma_f32_32x32x16_bf16 v[16:31], v[96:99], v[106:109], v[16:31]
	ds_read_b128 v[96:99], v118 offset:32768
	ds_read_b128 v[104:107], v119 offset:32768
	s_waitcnt lgkmcnt(0)
	v_mfma_f32_32x32x16_bf16 v[80:95], v[96:99], v[104:107], v[80:95]
	ds_read_b128 v[96:99], v118 offset:36864
	s_waitcnt lgkmcnt(0)
	v_mfma_f32_32x32x16_bf16 v[64:79], v[96:99], v[104:107], v[64:79]
	ds_read_b128 v[96:99], v118 offset:40960
	s_waitcnt lgkmcnt(0)
	v_mfma_f32_32x32x16_bf16 v[48:63], v[96:99], v[104:107], v[48:63]
	ds_read_b128 v[96:99], v118 offset:45056
	s_waitcnt lgkmcnt(0)
	v_mfma_f32_32x32x16_bf16 v[32:47], v[96:99], v[104:107], v[32:47]
	ds_read_b128 v[96:99], v118 offset:49152
	s_waitcnt lgkmcnt(0)
	v_mfma_f32_32x32x16_bf16 v[0:15], v[96:99], v[104:107], v[0:15]
	ds_read_b128 v[96:99], v118 offset:53248
	s_waitcnt lgkmcnt(0)
	v_mfma_f32_32x32x16_bf16 v[16:31], v[96:99], v[104:107], v[16:31]
	ds_read_b128 v[96:99], v124 offset:32768
	ds_read_b128 v[104:107], v120 offset:32768
	ds_read_b128 v[108:111], v124 offset:36864
	ds_read_b128 v[112:115], v124 offset:40960
	ds_read_b128 v[116:119], v124 offset:45056
	ds_read_b128 v[120:123], v124 offset:49152
	ds_read_b128 v[124:127], v124 offset:53248
	s_waitcnt vmcnt(0)
	s_waitcnt lgkmcnt(5)
	v_mfma_f32_32x32x16_bf16 v[80:95], v[96:99], v[104:107], v[80:95]
	v_lshl_add_u32 v99, v103, 5, s3
	v_or_b32_e32 v96, v99, v101
	v_ashrrev_i32_e32 v97, 31, v96
	s_mov_b32 s3, 0x20000
	s_waitcnt lgkmcnt(0)
	s_barrier
; DEV void epi_uq(f32x16 (&acc)[1][6], const Params& P, int layer, int batch, int m0, int head, int wid, int r32, int hi, char* lds) {
;   const int t = m0 + wid * 32 + r32;
;   const float rc = __builtin_amdgcn_rsqf((WS{P.ws}.ssq_cq()[t] + WS{P.ws}.ssq_cq()[TB + t] + WS{P.ws}.ssq_cq()[2 * TB + t] + WS{P.ws}.ssq_cq()[3 * TB + t]) * (1.f / 256.f) + EPS);
;   float s = 0.f;
; #pragma unroll
;   for (int ni = 0; ni < 6; ++ni)
; #pragma unroll
;     for (int r = 0; r < 16; ++r) { acc[0][ni][r] *= rc; s += acc[0][ni][r] * acc[0][ni][r]; }
	v_mfma_f32_32x32x16_bf16 v[64:79], v[108:111], v[104:107], v[64:79]
	v_lshl_add_u64 v[108:109], v[96:97], 2, s[8:9]
	v_add_co_u32_e32 v110, vcc, s93, v108
	v_lshlrev_b32_e32 v184, 4, v102
	s_nop 0
	v_addc_co_u32_e32 v111, vcc, 0, v109, vcc
	s_lshl_b32 s22, s2, 1
	v_mfma_f32_32x32x16_bf16 v[48:63], v[112:115], v[104:107], v[48:63]
	v_add_co_u32_e32 v112, vcc, s3, v108
	s_mov_b32 s3, 0x30000
	s_nop 0
	v_addc_co_u32_e32 v113, vcc, 0, v109, vcc
	v_add_co_u32_e32 v114, vcc, s3, v108
	v_mfma_f32_32x32x16_bf16 v[32:47], v[116:119], v[104:107], v[32:47]
	s_nop 0
	v_addc_co_u32_e32 v115, vcc, 0, v109, vcc
	flat_load_dword v97, v[108:109]
	flat_load_dword v98, v[110:111]
	s_nop 0
	flat_load_dword v108, v[112:113]
	flat_load_dword v109, v[114:115]
	s_movk_i32 s3, 0xfff
	s_waitcnt vmcnt(0) lgkmcnt(0)
	v_add_f32_e32 v97, v97, v98
	v_add_f32_e32 v97, v97, v108
	v_add_f32_e32 v97, v97, v109
	v_fmamk_f32 v97, v97, 0x3b800000, v227
	v_rsq_f32_e32 v98, v97
	v_mfma_f32_32x32x16_bf16 v[0:15], v[120:123], v[104:107], v[0:15]
	v_mul_f32_e32 v108, v81, v98
	v_mul_f32_e32 v97, v80, v98
	v_mul_f32_e32 v113, v86, v98
	v_mul_f32_e32 v86, v108, v108
	v_mul_f32_e32 v109, v82, v98
	v_fmac_f32_e32 v86, v97, v97
	v_mul_f32_e32 v110, v83, v98
	v_fmac_f32_e32 v86, v109, v109
	v_mul_f32_e32 v111, v84, v98
	v_fmac_f32_e32 v86, v110, v110
	v_mul_f32_e32 v112, v85, v98
	v_fmac_f32_e32 v86, v111, v111
	v_fmac_f32_e32 v86, v112, v112
	v_mul_f32_e32 v114, v87, v98
	v_fmac_f32_e32 v86, v113, v113
	v_mul_f32_e32 v115, v88, v98
	v_fmac_f32_e32 v86, v114, v114
	v_mul_f32_e32 v116, v89, v98
	v_fmac_f32_e32 v86, v115, v115
	v_mul_f32_e32 v117, v90, v98
	v_fmac_f32_e32 v86, v116, v116
	v_mul_f32_e32 v118, v91, v98
	v_fmac_f32_e32 v86, v117, v117
	v_mul_f32_e32 v119, v92, v98
	v_fmac_f32_e32 v86, v118, v118
	v_mul_f32_e32 v120, v93, v98
	v_fmac_f32_e32 v86, v119, v119
	v_mul_f32_e32 v121, v94, v98
	v_fmac_f32_e32 v86, v120, v120
	v_mul_f32_e32 v122, v95, v98
	v_fmac_f32_e32 v86, v121, v121
	v_mul_f32_e32 v123, v64, v98
	v_fmac_f32_e32 v86, v122, v122
	v_mfma_f32_32x32x16_bf16 v[16:31], v[124:127], v[104:107], v[16:31]
	v_mul_f32_e32 v124, v65, v98
	v_fmac_f32_e32 v86, v123, v123
	v_mul_f32_e32 v125, v66, v98
	v_fmac_f32_e32 v86, v124, v124
	v_mul_f32_e32 v126, v67, v98
	v_fmac_f32_e32 v86, v125, v125
	v_mul_f32_e32 v127, v68, v98
	v_fmac_f32_e32 v86, v126, v126
	v_mul_f32_e32 v128, v69, v98
	v_fmac_f32_e32 v86, v127, v127
	v_mul_f32_e32 v129, v70, v98
	v_fmac_f32_e32 v86, v128, v128
	v_mul_f32_e32 v130, v71, v98
	v_fmac_f32_e32 v86, v129, v129
	v_mul_f32_e32 v80, v72, v98
	v_fmac_f32_e32 v86, v130, v130
	v_mul_f32_e32 v81, v73, v98
	v_fmac_f32_e32 v86, v80, v80
	v_mul_f32_e32 v82, v74, v98
	v_fmac_f32_e32 v86, v81, v81
	v_mul_f32_e32 v83, v75, v98
	v_fmac_f32_e32 v86, v82, v82
	v_mul_f32_e32 v72, v76, v98
	v_fmac_f32_e32 v86, v83, v83
	v_mul_f32_e32 v73, v77, v98
	v_fmac_f32_e32 v86, v72, v72
	v_mul_f32_e32 v74, v78, v98
	v_fmac_f32_e32 v86, v73, v73
	v_mul_f32_e32 v75, v79, v98
	v_fmac_f32_e32 v86, v74, v74
	v_mul_f32_e32 v131, v36, v98
	v_mul_f32_e32 v132, v37, v98
	v_lshl_add_u64 v[36:37], s[10:11], 0, v[184:185]
	v_mul_f32_e32 v68, v48, v98
	v_mul_f32_e32 v70, v50, v98
	v_mul_f32_e32 v71, v51, v98
	v_mul_f32_e32 v66, v54, v98
	v_mul_f32_e32 v67, v55, v98
	v_mul_f32_e32 v54, v56, v98
	v_mul_f32_e32 v55, v57, v98
	v_mul_f32_e32 v56, v58, v98
	v_mul_f32_e32 v57, v59, v98
	v_mul_f32_e32 v50, v60, v98
	v_mul_f32_e32 v51, v61, v98
	v_fmac_f32_e32 v86, v75, v75
	flat_load_dwordx4 v[58:61], v[36:37] offset:1280
	global_load_dwordx4 v[194:197], v[36:37], off offset:1312
	global_load_dwordx4 v[198:201], v[36:37], off offset:1344
	global_load_dwordx4 v[202:205], v[36:37], off offset:1376
	global_load_dwordx4 v[206:209], v[36:37], off offset:1408
	global_load_dwordx4 v[210:213], v[36:37], off offset:1440
	global_load_dwordx4 v[214:217], v[36:37], off offset:1472
	global_load_dwordx4 v[218:221], v[36:37], off offset:1504
	global_load_dwordx4 v[222:225], v[36:37], off offset:1536
	global_load_dwordx4 v[232:235], v[36:37], off offset:1568
	global_load_dwordx4 v[236:239], v[36:37], off offset:1600
	global_load_dwordx4 v[240:243], v[36:37], off offset:1632
	global_load_dwordx4 v[244:247], v[36:37], off offset:1664
	global_load_dwordx4 v[248:251], v[36:37], off offset:1696
	global_load_dwordx4 v[170:173], v[36:37], off offset:1728
	global_load_dwordx4 v[174:177], v[36:37], off offset:1760
	v_mul_f32_e32 v69, v49, v98
	v_fmac_f32_e32 v86, v68, v68
	v_fmac_f32_e32 v86, v69, v69
	v_fmac_f32_e32 v86, v70, v70
	v_mul_f32_e32 v64, v52, v98
	v_fmac_f32_e32 v86, v71, v71
	v_mul_f32_e32 v65, v53, v98
	v_fmac_f32_e32 v86, v64, v64
	v_fmac_f32_e32 v86, v65, v65
	v_fmac_f32_e32 v86, v66, v66
	v_fmac_f32_e32 v86, v67, v67
	v_fmac_f32_e32 v86, v54, v54
	v_fmac_f32_e32 v86, v55, v55
	v_fmac_f32_e32 v86, v56, v56
	v_fmac_f32_e32 v86, v57, v57
	v_fmac_f32_e32 v86, v50, v50
	v_mul_f32_e32 v52, v62, v98
	v_fmac_f32_e32 v86, v51, v51
	v_mul_f32_e32 v53, v63, v98
	v_fmac_f32_e32 v86, v52, v52
	v_mul_f32_e32 v48, v32, v98
	v_fmac_f32_e32 v86, v53, v53
	v_mul_f32_e32 v33, v33, v98
	v_fmac_f32_e32 v86, v48, v48
	v_mul_f32_e32 v49, v34, v98
	v_fmac_f32_e32 v86, v33, v33
	v_mul_f32_e32 v35, v35, v98
	v_fmac_f32_e32 v86, v49, v49
	v_fmac_f32_e32 v86, v35, v35
	v_fmac_f32_e32 v86, v131, v131
	v_fmac_f32_e32 v86, v132, v132
	v_mul_f32_e32 v133, v38, v98
	v_fmac_f32_e32 v86, v133, v133
	v_mul_f32_e32 v134, v39, v98
	v_fmac_f32_e32 v86, v134, v134
	v_mul_f32_e32 v135, v40, v98
	v_fmac_f32_e32 v86, v135, v135
	v_mul_f32_e32 v136, v41, v98
	v_fmac_f32_e32 v86, v136, v136
	v_mul_f32_e32 v137, v42, v98
	v_fmac_f32_e32 v86, v137, v137
; DEV void epi_uq(f32x16 (&acc)[1][6], const Params& P, int layer, int batch, int m0, int head, int wid, int r32, int hi, char* lds) {
;     ...
;   float s = 0.f;
; #pragma unroll
;   for (int ni = 0; ni < 6; ++ni)
; #pragma unroll
;     for (int r = 0; r < 16; ++r) { acc[0][ni][r] *= rc; s += acc[0][ni][r] * acc[0][ni][r]; }
;   s = swapsum(s);
;   constexpr float SCQ = 0.07216878364870323f * LOG2E;
;   const float inv = __builtin_amdgcn_rsqf(s * (1.f / 192.f) + EPS) * SCQ;
;   const float* g = WS{P.ws}.consts() + layer * 1024 + 320;
;   char* slab = lds + wid * 12800; char* dst = slab + r32 * 400;
; #pragma unroll
;   for (int ni = 0; ni < 4; ++ni)
; #pragma unroll
;     for (int r4 = 0; r4 < 4; ++r4) {
;       const int c = ni * 32 + r4 * 8 + hi * 4;
;       const float4 gg = *reinterpret_cast<const float4*>(g + c);
;       const f32x16& a = acc[0][ni];
;       st4lds(dst, c, a[r4 * 4] * inv * gg.x, a[r4 * 4 + 1] * inv * gg.y, a[r4 * 4 + 2] * inv * gg.z, a[r4 * 4 + 3] * inv * gg.w);
;     }
	v_mul_f32_e32 v138, v43, v98
	v_fmac_f32_e32 v86, v138, v138
	v_mul_f32_e32 v139, v44, v98
	v_fmac_f32_e32 v86, v139, v139
	v_mul_f32_e32 v140, v45, v98
	v_mul_f32_e32 v34, v14, v98
	v_mul_lo_u32 v14, v103, s99
	v_fmac_f32_e32 v86, v140, v140
	v_mul_f32_e32 v141, v46, v98
	v_mul_f32_e32 v32, v15, v98
	v_add_u32_e32 v46, 0, v14
	v_mov_b32_e32 v14, v2
	v_mov_b32_e32 v15, v18
	v_mov_b32_e32 v18, v3
	v_mov_b32_e32 v2, v0
	v_mov_b32_e32 v3, v16
	v_fmac_f32_e32 v86, v141, v141
	v_mul_f32_e32 v47, v47, v98
	v_pk_mul_f32 v[42:43], v[2:3], v[98:99] op_sel_hi:[1,0]
	v_mov_b32_e32 v16, v1
	v_fmac_f32_e32 v86, v47, v47
	v_pk_mul_f32 v[84:85], v[42:43], v[42:43]
	v_pk_mul_f32 v[44:45], v[16:17], v[98:99] op_sel_hi:[1,0]
	v_pk_mul_f32 v[14:15], v[14:15], v[98:99] op_sel_hi:[1,0]
	v_add_f32_e32 v0, v84, v86
	v_pk_mul_f32 v[86:87], v[44:45], v[44:45]
	v_pk_mul_f32 v[76:77], v[14:15], v[14:15]
	v_pk_mul_f32 v[40:41], v[18:19], v[98:99] op_sel_hi:[1,0]
	v_add_f32_e32 v0, v86, v0
	v_pk_mul_f32 v[78:79], v[40:41], v[40:41]
	v_add_f32_e32 v0, v76, v0
	v_add_f32_e32 v16, v78, v0
	v_mov_b32_e32 v0, v6
	v_mov_b32_e32 v1, v22
	v_mov_b32_e32 v22, v7
	v_mov_b32_e32 v6, v4
	v_mov_b32_e32 v7, v20
	v_pk_mul_f32 v[6:7], v[6:7], v[98:99] op_sel_hi:[1,0]
	v_mov_b32_e32 v20, v5
	v_pk_mul_f32 v[92:93], v[6:7], v[6:7]
	v_pk_mul_f32 v[4:5], v[20:21], v[98:99] op_sel_hi:[1,0]
	v_pk_mul_f32 v[0:1], v[0:1], v[98:99] op_sel_hi:[1,0]
	v_add_f32_e32 v16, v92, v16
	v_pk_mul_f32 v[20:21], v[4:5], v[4:5]
	v_pk_mul_f32 v[88:89], v[0:1], v[0:1]
	v_pk_mul_f32 v[2:3], v[22:23], v[98:99] op_sel_hi:[1,0]
	v_add_f32_e32 v16, v20, v16
	v_pk_mul_f32 v[90:91], v[2:3], v[2:3]
	v_add_f32_e32 v16, v88, v16
	v_add_f32_e32 v18, v90, v16
	v_mov_b32_e32 v16, v10
	v_mov_b32_e32 v17, v26
	v_pk_mul_f32 v[22:23], v[16:17], v[98:99] op_sel_hi:[1,0]
	v_mov_b32_e32 v16, v8
	v_mov_b32_e32 v17, v24
	v_pk_mul_f32 v[38:39], v[16:17], v[98:99] op_sel_hi:[1,0]
	v_mov_b32_e32 v24, v9
	v_pk_mul_f32 v[104:105], v[38:39], v[38:39]
	v_pk_mul_f32 v[24:25], v[24:25], v[98:99] op_sel_hi:[1,0]
	v_mov_b32_e32 v26, v11
	v_add_f32_e32 v16, v104, v18
	v_pk_mul_f32 v[8:9], v[24:25], v[24:25]
	v_pk_mul_f32 v[94:95], v[22:23], v[22:23]
	v_pk_mul_f32 v[26:27], v[26:27], v[98:99] op_sel_hi:[1,0]
	v_add_f32_e32 v8, v8, v16
	v_mov_b32_e32 v16, v12
	v_mov_b32_e32 v17, v28
	v_pk_mul_f32 v[10:11], v[26:27], v[26:27]
	v_add_f32_e32 v8, v94, v8
	v_pk_mul_f32 v[16:17], v[16:17], v[98:99] op_sel_hi:[1,0]
	v_mov_b32_e32 v28, v13
	v_add_f32_e32 v8, v10, v8
	v_pk_mul_f32 v[106:107], v[16:17], v[16:17]
	v_pk_mul_f32 v[18:19], v[28:29], v[98:99] op_sel_hi:[1,0]
	v_add_f32_e32 v8, v106, v8
	v_pk_mul_f32 v[12:13], v[18:19], v[18:19]
	v_pk_mul_f32 v[30:31], v[30:31], v[98:99] op_sel_hi:[1,0]
	v_add_f32_e32 v8, v12, v8
	v_fmac_f32_e32 v8, v34, v34
	v_fmac_f32_e32 v8, v32, v32
	v_add_f32_e32 v8, v85, v8
	v_add_f32_e32 v8, v87, v8
	v_add_f32_e32 v8, v77, v8
	v_add_f32_e32 v8, v79, v8
	v_add_f32_e32 v8, v93, v8
	v_add_f32_e32 v8, v21, v8
	v_add_f32_e32 v8, v89, v8
	v_add_f32_e32 v8, v91, v8
	v_add_f32_e32 v8, v105, v8
	v_add_f32_e32 v8, v9, v8
	v_add_f32_e32 v8, v95, v8
	v_add_f32_e32 v8, v11, v8
	v_add_f32_e32 v8, v107, v8
	v_pk_mul_f32 v[62:63], v[30:31], v[30:31]
	v_add_f32_e32 v8, v13, v8
	v_add_f32_e32 v8, v62, v8
	v_add_f32_e32 v8, v63, v8
	v_mov_b32_e32 v9, v8
	s_nop 1
	v_permlane32_swap_b32_e32 v8, v9
	v_add_f32_e32 v8, v8, v9
	v_fmamk_f32 v8, v8, 0x3baaaaab, v227
	v_rsq_f32_e32 v8, v8
	v_mul_u32_u24_e32 v9, 0x190, v101
	v_lshlrev_b32_e32 v10, 3, v102
	v_add3_u32 v21, v46, v9, v10
	v_mul_f32_e32 v20, 0x3dd53b94, v8
	v_mul_f32_e32 v8, v97, v20
	v_mul_f32_e32 v9, v108, v20
	s_waitcnt vmcnt(0) lgkmcnt(0)
	v_mul_f32_e32 v8, v58, v8
	v_mul_f32_e32 v9, v59, v9
	v_mul_f32_e32 v10, v109, v20
	v_mul_f32_e32 v11, v110, v20
	v_mul_f32_e32 v10, v60, v10
	v_mul_f32_e32 v11, v61, v11
	v_cvt_pk_bf16_f32 v8, v8, v9
	v_cvt_pk_bf16_f32 v9, v10, v11
	ds_write_b64 v21, v[8:9]
	v_mul_f32_e32 v12, v111, v20
	v_mul_f32_e32 v13, v116, v20
	v_mul_f32_e32 v28, v117, v20
	v_mul_f32_e32 v29, v118, v20
	v_lshlrev_b32_e32 v184, 5, v102
	v_pk_mul_f32 v[14:15], v[14:15], v[20:21] op_sel_hi:[1,0]
	v_pk_mul_f32 v[40:41], v[40:41], v[20:21] op_sel_hi:[1,0]
	v_pk_mul_f32 v[6:7], v[6:7], v[20:21] op_sel_hi:[1,0]
	v_pk_mul_f32 v[4:5], v[4:5], v[20:21] op_sel_hi:[1,0]
	v_pk_mul_f32 v[0:1], v[0:1], v[20:21] op_sel_hi:[1,0]
	v_pk_mul_f32 v[2:3], v[2:3], v[20:21] op_sel_hi:[1,0]
	v_pk_mul_f32 v[38:39], v[38:39], v[20:21] op_sel_hi:[1,0]
	v_pk_mul_f32 v[24:25], v[24:25], v[20:21] op_sel_hi:[1,0]
	v_pk_mul_f32 v[22:23], v[22:23], v[20:21] op_sel_hi:[1,0]
	v_pk_mul_f32 v[26:27], v[26:27], v[20:21] op_sel_hi:[1,0]
	v_pk_mul_f32 v[16:17], v[16:17], v[20:21] op_sel_hi:[1,0]
	v_pk_mul_f32 v[18:19], v[18:19], v[20:21] op_sel_hi:[1,0]
	v_mul_f32_e32 v8, v194, v12
	v_mul_f32_e32 v12, v112, v20
	v_mul_f32_e32 v9, v12, v195
	v_mul_f32_e32 v12, v113, v20
	v_mul_f32_e32 v10, v12, v196
	v_mul_f32_e32 v12, v114, v20
	v_mul_f32_e32 v11, v12, v197
	v_cvt_pk_bf16_f32 v8, v8, v9
	v_cvt_pk_bf16_f32 v9, v10, v11
	ds_write_b64 v21, v[8:9] offset:16
	v_mul_f32_e32 v12, v115, v20
	v_mul_f32_e32 v8, v12, v198
	v_mul_f32_e32 v9, v13, v199
	v_mul_f32_e32 v10, v28, v200
	v_mul_f32_e32 v11, v29, v201
	v_cvt_pk_bf16_f32 v8, v8, v9
	v_cvt_pk_bf16_f32 v9, v10, v11
	ds_write_b64 v21, v[8:9] offset:32
	v_mul_f32_e32 v12, v119, v20
	v_mul_f32_e32 v13, v120, v20
	v_mul_f32_e32 v28, v121, v20
	v_mul_f32_e32 v29, v122, v20
	v_mul_f32_e32 v8, v12, v202
	v_mul_f32_e32 v9, v13, v203
	v_mul_f32_e32 v10, v28, v204
	v_mul_f32_e32 v11, v29, v205
	v_cvt_pk_bf16_f32 v8, v8, v9
	v_cvt_pk_bf16_f32 v9, v10, v11
; DEV void epi_uq(f32x16 (&acc)[1][6], const Params& P, int layer, int batch, int m0, int head, int wid, int r32, int hi, char* lds) {
;     ...
; #pragma unroll
;   for (int ni = 0; ni < 4; ++ni)
; #pragma unroll
;     for (int r4 = 0; r4 < 4; ++r4) {
;       const int c = ni * 32 + r4 * 8 + hi * 4;
;       const float4 gg = *reinterpret_cast<const float4*>(g + c);
;       const f32x16& a = acc[0][ni];
;       st4lds(dst, c, a[r4 * 4] * inv * gg.x, a[r4 * 4 + 1] * inv * gg.y, a[r4 * 4 + 2] * inv * gg.z, a[r4 * 4 + 3] * inv * gg.w);
;     }
;   const int pos = batch ? t : (t & 4095);
;   const float2* rp = WS{P.ws}.rope() + (long)pos * 32;
; #pragma unroll
;   for (int r4 = 0; r4 < 4; ++r4) {
;     const int i = r4 * 8 + hi * 4;
;     const float4 g1 = *reinterpret_cast<const float4*>(g + 128 + i), g2 = *reinterpret_cast<const float4*>(g + 160 + i);
;     const float4 cs01 = *reinterpret_cast<const float4*>(rp + i), cs23 = *reinterpret_cast<const float4*>(rp + i + 2);
;     const float x1[4] = {acc[0][4][r4 * 4] * inv * g1.x, acc[0][4][r4 * 4 + 1] * inv * g1.y, acc[0][4][r4 * 4 + 2] * inv * g1.z, acc[0][4][r4 * 4 + 3] * inv * g1.w};
;     const float x2[4] = {acc[0][5][r4 * 4] * inv * g2.x, acc[0][5][r4 * 4 + 1] * inv * g2.y, acc[0][5][r4 * 4 + 2] * inv * g2.z, acc[0][5][r4 * 4 + 3] * inv * g2.w};
;     const float cc[4] = {cs01.x, cs01.z, cs23.x, cs23.z}, sn[4] = {cs01.y, cs01.w, cs23.y, cs23.w};
;     st4lds(dst, 128 + i, x1[0] * cc[0] - x2[0] * sn[0], x1[1] * cc[1] - x2[1] * sn[1], x1[2] * cc[2] - x2[2] * sn[2], x1[3] * cc[3] - x2[3] * sn[3]);
;     st4lds(dst, 160 + i, x1[0] * sn[0] + x2[0] * cc[0], x1[1] * sn[1] + x2[1] * cc[1], x1[2] * sn[2] + x2[2] * cc[2], x1[3] * sn[3] + x2[3] * cc[3]);
;   }
;   slab_flush<24, 400>(slab, WS{P.ws}.QB() + (long)(m0 + wid * 32) * 768 + head * 192, 768, hi * 32 + r32);
	ds_write_b64 v21, v[8:9] offset:48
	v_mul_f32_e32 v12, v123, v20
	v_mul_f32_e32 v13, v124, v20
	v_mul_f32_e32 v28, v125, v20
	v_mul_f32_e32 v29, v126, v20
	v_mul_f32_e32 v8, v12, v206
	v_mul_f32_e32 v9, v13, v207
	v_mul_f32_e32 v10, v28, v208
	v_mul_f32_e32 v11, v29, v209
	v_cvt_pk_bf16_f32 v8, v8, v9
	v_cvt_pk_bf16_f32 v9, v10, v11
	ds_write_b64 v21, v[8:9] offset:64
	v_mul_f32_e32 v12, v127, v20
	v_mul_f32_e32 v13, v128, v20
	v_mul_f32_e32 v28, v129, v20
	v_mul_f32_e32 v29, v130, v20
	v_mul_f32_e32 v8, v12, v210
	v_mul_f32_e32 v9, v13, v211
	v_mul_f32_e32 v10, v28, v212
	v_mul_f32_e32 v11, v29, v213
	v_cvt_pk_bf16_f32 v8, v8, v9
	v_cvt_pk_bf16_f32 v9, v10, v11
	ds_write_b64 v21, v[8:9] offset:80
	v_mul_f32_e32 v12, v80, v20
	v_mul_f32_e32 v13, v81, v20
	v_mul_f32_e32 v28, v82, v20
	v_mul_f32_e32 v29, v83, v20
	v_mul_f32_e32 v8, v12, v214
	v_mul_f32_e32 v9, v13, v215
	v_mul_f32_e32 v10, v28, v216
	v_mul_f32_e32 v11, v29, v217
	v_cvt_pk_bf16_f32 v8, v8, v9
	v_cvt_pk_bf16_f32 v9, v10, v11
	ds_write_b64 v21, v[8:9] offset:96
	v_mul_f32_e32 v12, v72, v20
	v_mul_f32_e32 v13, v73, v20
	v_mul_f32_e32 v28, v74, v20
	v_mul_f32_e32 v29, v75, v20
	v_mul_f32_e32 v8, v12, v218
	v_mul_f32_e32 v9, v13, v219
	v_mul_f32_e32 v10, v28, v220
	v_mul_f32_e32 v11, v29, v221
	v_cvt_pk_bf16_f32 v8, v8, v9
	v_cvt_pk_bf16_f32 v9, v10, v11
	ds_write_b64 v21, v[8:9] offset:112
	v_mul_f32_e32 v12, v68, v20
	v_mul_f32_e32 v13, v69, v20
	v_mul_f32_e32 v28, v70, v20
	v_mul_f32_e32 v29, v71, v20
	v_mul_f32_e32 v8, v12, v222
	v_mul_f32_e32 v9, v13, v223
	v_mul_f32_e32 v10, v28, v224
	v_mul_f32_e32 v11, v29, v225
	v_cvt_pk_bf16_f32 v8, v8, v9
	v_cvt_pk_bf16_f32 v9, v10, v11
	ds_write_b64 v21, v[8:9] offset:128
	v_mul_f32_e32 v12, v64, v20
	v_mul_f32_e32 v13, v65, v20
	v_mul_f32_e32 v28, v66, v20
	v_mul_f32_e32 v29, v67, v20
	v_mul_f32_e32 v8, v12, v232
	v_mul_f32_e32 v9, v13, v233
	v_mul_f32_e32 v10, v28, v234
	v_mul_f32_e32 v11, v29, v235
	v_cvt_pk_bf16_f32 v8, v8, v9
	v_cvt_pk_bf16_f32 v9, v10, v11
	ds_write_b64 v21, v[8:9] offset:144
	v_mul_f32_e32 v12, v54, v20
	v_mul_f32_e32 v13, v55, v20
	v_mul_f32_e32 v28, v56, v20
	v_mul_f32_e32 v29, v57, v20
	v_mul_f32_e32 v8, v12, v236
	v_mul_f32_e32 v9, v13, v237
	v_mul_f32_e32 v10, v28, v238
	v_mul_f32_e32 v11, v29, v239
	v_cvt_pk_bf16_f32 v8, v8, v9
	v_cvt_pk_bf16_f32 v9, v10, v11
	ds_write_b64 v21, v[8:9] offset:160
	v_mul_f32_e32 v12, v50, v20
	v_mul_f32_e32 v13, v51, v20
	v_mul_f32_e32 v28, v52, v20
	v_mul_f32_e32 v29, v53, v20
	v_mul_f32_e32 v8, v12, v240
	v_mul_f32_e32 v9, v13, v241
	v_mul_f32_e32 v10, v28, v242
	v_mul_f32_e32 v11, v29, v243
	v_cvt_pk_bf16_f32 v8, v8, v9
	v_cvt_pk_bf16_f32 v9, v10, v11
	ds_write_b64 v21, v[8:9] offset:176
	v_mul_f32_e32 v12, v48, v20
	v_mul_f32_e32 v13, v33, v20
	v_mul_f32_e32 v28, v49, v20
	v_mul_f32_e32 v29, v35, v20
	v_mul_f32_e32 v8, v12, v244
	v_mul_f32_e32 v9, v13, v245
	v_mul_f32_e32 v10, v28, v246
	v_mul_f32_e32 v11, v29, v247
	v_cvt_pk_bf16_f32 v8, v8, v9
	v_cvt_pk_bf16_f32 v9, v10, v11
	ds_write_b64 v21, v[8:9] offset:192
	v_mul_f32_e32 v12, v131, v20
	v_mul_f32_e32 v13, v132, v20
	v_mul_f32_e32 v28, v133, v20
	v_mul_f32_e32 v29, v134, v20
	v_mul_f32_e32 v8, v12, v248
	v_mul_f32_e32 v9, v13, v249
	v_mul_f32_e32 v10, v28, v250
	v_mul_f32_e32 v11, v29, v251
	v_cvt_pk_bf16_f32 v8, v8, v9
	v_cvt_pk_bf16_f32 v9, v10, v11
	ds_write_b64 v21, v[8:9] offset:208
	v_mul_f32_e32 v12, v135, v20
	v_mul_f32_e32 v13, v136, v20
	v_mul_f32_e32 v28, v137, v20
	v_mul_f32_e32 v29, v138, v20
	v_mul_f32_e32 v8, v12, v170
	v_mul_f32_e32 v9, v13, v171
	v_mul_f32_e32 v10, v28, v172
	v_mul_f32_e32 v11, v29, v173
	v_cvt_pk_bf16_f32 v8, v8, v9
	v_cvt_pk_bf16_f32 v9, v10, v11
	ds_write_b64 v21, v[8:9] offset:224
	v_mul_f32_e32 v12, v139, v20
	v_mul_f32_e32 v13, v140, v20
	v_mul_f32_e32 v28, v141, v20
	v_mul_f32_e32 v29, v47, v20
	v_mul_f32_e32 v8, v12, v174
	v_bitop3_b32 v12, v99, s3, v101 bitop3:0xc8
	v_cndmask_b32_e64 v12, v96, v12, s[26:27]
	v_mul_f32_e32 v9, v13, v175
	v_ashrrev_i32_e32 v13, 31, v12
	v_mul_f32_e32 v10, v28, v176
	v_mul_f32_e32 v11, v29, v177
	v_cvt_pk_bf16_f32 v8, v8, v9
	v_cvt_pk_bf16_f32 v9, v10, v11
	ds_write_b64 v21, v[8:9] offset:240
	v_lshlrev_b64 v[12:13], 8, v[12:13]
	flat_load_dwordx4 v[8:11], v[36:37] offset:1792
	flat_load_dwordx4 v[48:51], v[36:37] offset:1920
	v_lshl_add_u64 v[12:13], s[12:13], 0, v[12:13]
	v_lshl_add_u64 v[28:29], v[12:13], 0, v[184:185]
	flat_load_dwordx4 v[52:55], v[28:29]
	flat_load_dwordx4 v[56:59], v[28:29] offset:16
	v_pk_mul_f32 v[12:13], v[42:43], v[20:21] op_sel_hi:[1,0]
	v_pk_mul_f32 v[42:43], v[44:45], v[20:21] op_sel_hi:[1,0]
	s_waitcnt vmcnt(0) lgkmcnt(0)
	v_mov_b32_e32 v44, v8
	v_mov_b32_e32 v45, v48
	v_mov_b32_e32 v48, v9
	v_mov_b32_e32 v8, v10
	v_mov_b32_e32 v9, v50
	v_mov_b32_e32 v50, v11
	v_pk_mul_f32 v[10:11], v[12:13], v[44:45]
	v_pk_mul_f32 v[12:13], v[42:43], v[48:49]
	v_pk_mul_f32 v[8:9], v[14:15], v[8:9]
	v_pk_mul_f32 v[14:15], v[40:41], v[50:51]
	v_pk_mul_f32 v[40:41], v[10:11], v[52:53]
	v_pk_mul_f32 v[42:43], v[12:13], v[54:55]
	v_pk_mul_f32 v[44:45], v[8:9], v[56:57]
	v_pk_mul_f32 v[48:49], v[14:15], v[58:59]
	v_pk_mul_f32 v[10:11], v[10:11], v[52:53] op_sel:[1,0] op_sel_hi:[0,1]
	v_pk_mul_f32 v[12:13], v[12:13], v[54:55] op_sel:[1,0] op_sel_hi:[0,1]
	v_pk_mul_f32 v[8:9], v[8:9], v[56:57] op_sel:[1,0] op_sel_hi:[0,1]
	v_pk_mul_f32 v[14:15], v[14:15], v[58:59] op_sel:[1,0] op_sel_hi:[0,1]
	v_sub_f32_e32 v33, v40, v41
	v_sub_f32_e32 v35, v42, v43
	v_sub_f32_e32 v40, v44, v45
	v_sub_f32_e32 v41, v48, v49
	v_add_f32_e32 v10, v10, v11
	v_add_f32_e32 v11, v12, v13
	v_add_f32_e32 v12, v8, v9
	v_cvt_pk_bf16_f32 v8, v33, v35
	v_cvt_pk_bf16_f32 v9, v40, v41
	v_add_f32_e32 v13, v14, v15
	ds_write_b64 v21, v[8:9] offset:256
	v_cvt_pk_bf16_f32 v8, v10, v11
	v_cvt_pk_bf16_f32 v9, v12, v13
	ds_write_b64 v21, v[8:9] offset:320
	flat_load_dwordx4 v[8:11], v[36:37] offset:1824
	flat_load_dwordx4 v[12:15], v[36:37] offset:1952
	flat_load_dwordx4 v[40:43], v[28:29] offset:64
	flat_load_dwordx4 v[48:51], v[28:29] offset:80
	v_and_b32_e32 v33, 63, v100
	v_mul_lo_u16_e32 v35, 43, v33
	v_or_b32_e32 v47, 0xc0, v33
	v_or_b32_e32 v52, 0x1c0, v33
	v_or_b32_e32 v53, 0x280, v33
	v_or_b32_e32 v54, 0x240, v33
	v_or_b32_e32 v55, 0x2c0, v33
	v_lshrrev_b16_e32 v35, 10, v35
	v_mul_lo_u16_e32 v56, 0xab, v47
	v_mul_u32_u24_e32 v60, 0xaab, v52
	v_mul_u32_u24_e32 v62, 0xaab, v54
	v_mul_u32_u24_e32 v63, 0xaab, v53
	v_mul_u32_u24_e32 v64, 0xaab, v55
	v_lshrrev_b16_e32 v56, 12, v56
	v_mul_u32_u24_e32 v65, 0x190, v35
	v_lshrrev_b32_e32 v71, 16, v63
	s_waitcnt vmcnt(0) lgkmcnt(0)
; DEV void epi_uq(f32x16 (&acc)[1][6], const Params& P, int layer, int batch, int m0, int head, int wid, int r32, int hi, char* lds) {
;     ...
;   const int pos = batch ? t : (t & 4095);
;   const float2* rp = WS{P.ws}.rope() + (long)pos * 32;
; #pragma unroll
;   for (int r4 = 0; r4 < 4; ++r4) {
;     const int i = r4 * 8 + hi * 4;
;     const float4 g1 = *reinterpret_cast<const float4*>(g + 128 + i), g2 = *reinterpret_cast<const float4*>(g + 160 + i);
;     const float4 cs01 = *reinterpret_cast<const float4*>(rp + i), cs23 = *reinterpret_cast<const float4*>(rp + i + 2);
;     const float x1[4] = {acc[0][4][r4 * 4] * inv * g1.x, acc[0][4][r4 * 4 + 1] * inv * g1.y, acc[0][4][r4 * 4 + 2] * inv * g1.z, acc[0][4][r4 * 4 + 3] * inv * g1.w};
;     const float x2[4] = {acc[0][5][r4 * 4] * inv * g2.x, acc[0][5][r4 * 4 + 1] * inv * g2.y, acc[0][5][r4 * 4 + 2] * inv * g2.z, acc[0][5][r4 * 4 + 3] * inv * g2.w};
;     const float cc[4] = {cs01.x, cs01.z, cs23.x, cs23.z}, sn[4] = {cs01.y, cs01.w, cs23.y, cs23.w};
;     st4lds(dst, 128 + i, x1[0] * cc[0] - x2[0] * sn[0], x1[1] * cc[1] - x2[1] * sn[1], x1[2] * cc[2] - x2[2] * sn[2], x1[3] * cc[3] - x2[3] * sn[3]);
;     st4lds(dst, 160 + i, x1[0] * sn[0] + x2[0] * cc[0], x1[1] * sn[1] + x2[1] * cc[1], x1[2] * sn[2] + x2[2] * cc[2], x1[3] * sn[3] + x2[3] * cc[3]);
;   }
;   slab_flush<24, 400>(slab, WS{P.ws}.QB() + (long)(m0 + wid * 32) * 768 + head * 192, 768, hi * 32 + r32);
	v_mov_b32_e32 v44, v8
	v_mov_b32_e32 v45, v12
	v_mov_b32_e32 v12, v9
	v_mov_b32_e32 v8, v10
	v_mov_b32_e32 v9, v14
	v_mov_b32_e32 v14, v11
	v_pk_mul_f32 v[6:7], v[6:7], v[44:45]
	v_pk_mul_f32 v[4:5], v[4:5], v[12:13]
	v_pk_mul_f32 v[0:1], v[0:1], v[8:9]
	v_pk_mul_f32 v[2:3], v[2:3], v[14:15]
	v_pk_mul_f32 v[8:9], v[6:7], v[40:41]
	v_pk_mul_f32 v[10:11], v[4:5], v[42:43]
	v_pk_mul_f32 v[12:13], v[0:1], v[48:49]
	v_pk_mul_f32 v[14:15], v[2:3], v[50:51]
	v_pk_mul_f32 v[4:5], v[4:5], v[42:43] op_sel:[1,0] op_sel_hi:[0,1]
	v_pk_mul_f32 v[0:1], v[0:1], v[48:49] op_sel:[1,0] op_sel_hi:[0,1]
	v_pk_mul_f32 v[6:7], v[6:7], v[40:41] op_sel:[1,0] op_sel_hi:[0,1]
	v_pk_mul_f32 v[2:3], v[2:3], v[50:51] op_sel:[1,0] op_sel_hi:[0,1]
	v_sub_f32_e32 v8, v8, v9
	v_sub_f32_e32 v9, v10, v11
	v_sub_f32_e32 v10, v12, v13
	v_sub_f32_e32 v11, v14, v15
	v_add_f32_e32 v4, v4, v5
	v_add_f32_e32 v5, v0, v1
	v_cvt_pk_bf16_f32 v0, v8, v9
	v_cvt_pk_bf16_f32 v1, v10, v11
	v_add_f32_e32 v6, v6, v7
	v_add_f32_e32 v2, v2, v3
	ds_write_b64 v21, v[0:1] offset:272
	v_cvt_pk_bf16_f32 v0, v6, v4
	v_cvt_pk_bf16_f32 v1, v5, v2
	ds_write_b64 v21, v[0:1] offset:336
	flat_load_dwordx4 v[12:15], v[36:37] offset:1856
	flat_load_dwordx4 v[8:11], v[36:37] offset:1984
	flat_load_dwordx4 v[0:3], v[28:29] offset:128
	flat_load_dwordx4 v[4:7], v[28:29] offset:144
	v_or_b32_e32 v44, 64, v33
	v_or_b32_e32 v45, 0x80, v33
	v_mul_lo_u16_e32 v42, 43, v44
	v_mul_lo_u16_e32 v43, 0xab, v45
	v_lshrrev_b16_e32 v66, 10, v42
	v_lshrrev_b16_e32 v67, 12, v43
	v_or_b32_e32 v48, 0x100, v33
	v_or_b32_e32 v49, 0x180, v33
	v_or_b32_e32 v50, 0x140, v33
	v_or_b32_e32 v51, 0x200, v33
	v_mul_u32_u24_e32 v57, 0xaab, v48
	v_mul_u32_u24_e32 v58, 0xaab, v50
	v_mul_u32_u24_e32 v59, 0xaab, v49
	v_mul_u32_u24_e32 v61, 0xaab, v51
	v_mad_i32_i24 v33, v35, s58, v33
	v_lshrrev_b32_e32 v57, 16, v57
	v_lshrrev_b32_e32 v68, 16, v58
	v_lshrrev_b32_e32 v69, 16, v59
	v_perm_b32 v58, v59, v58, s44
	v_lshrrev_b32_e32 v59, 16, v60
	v_lshrrev_b32_e32 v70, 16, v61
	v_perm_b32 v60, v61, v60, s44
	v_lshrrev_b32_e32 v61, 16, v62
	v_perm_b32 v62, v63, v62, s44
	v_lshrrev_b32_e32 v63, 16, v64
	v_lshlrev_b32_e32 v64, 4, v33
	v_mul_u32_u24_e32 v35, 0x300, v35
	v_lshlrev_b32_e32 v184, 1, v35
	v_mov_b32_e32 v35, v30
	v_mov_b64_e32 v[40:41], s[14:15]
	v_mad_i64_i32 v[40:41], s[2:3], v99, s39, v[40:41]
	v_lshl_add_u64 v[40:41], v[40:41], 0, s[22:23]
	v_mad_i32_i24 v55, v63, s58, v55
	v_lshlrev_b32_e32 v80, 4, v55
	s_waitcnt vmcnt(0) lgkmcnt(0)
	v_mov_b32_e32 v42, v12
	v_mov_b32_e32 v43, v8
	v_mov_b32_e32 v8, v13
	v_mov_b32_e32 v12, v14
	v_mov_b32_e32 v13, v10
	v_mov_b32_e32 v10, v15
	v_pk_mul_f32 v[14:15], v[38:39], v[42:43]
	v_pk_mul_f32 v[8:9], v[24:25], v[8:9]
	v_pk_mul_f32 v[12:13], v[22:23], v[12:13]
	v_pk_mul_f32 v[10:11], v[26:27], v[10:11]
	v_pk_mul_f32 v[22:23], v[14:15], v[0:1]
	v_pk_mul_f32 v[24:25], v[8:9], v[2:3]
	v_pk_mul_f32 v[26:27], v[12:13], v[4:5]
	v_pk_mul_f32 v[38:39], v[10:11], v[6:7]
	v_pk_mul_f32 v[0:1], v[14:15], v[0:1] op_sel:[1,0] op_sel_hi:[0,1]
	v_pk_mul_f32 v[2:3], v[8:9], v[2:3] op_sel:[1,0] op_sel_hi:[0,1]
	v_pk_mul_f32 v[4:5], v[12:13], v[4:5] op_sel:[1,0] op_sel_hi:[0,1]
	v_pk_mul_f32 v[6:7], v[10:11], v[6:7] op_sel:[1,0] op_sel_hi:[0,1]
	v_sub_f32_e32 v8, v22, v23
	v_sub_f32_e32 v9, v24, v25
	v_sub_f32_e32 v10, v26, v27
	v_sub_f32_e32 v11, v38, v39
	v_add_f32_e32 v12, v0, v1
	v_cvt_pk_bf16_f32 v0, v8, v9
	v_cvt_pk_bf16_f32 v1, v10, v11
	v_add_f32_e32 v2, v2, v3
	v_add_f32_e32 v3, v4, v5
	v_add_f32_e32 v4, v6, v7
	ds_write_b64 v21, v[0:1] offset:288
	v_cvt_pk_bf16_f32 v0, v12, v2
	v_cvt_pk_bf16_f32 v1, v3, v4
	ds_write_b64 v21, v[0:1] offset:352
	flat_load_dwordx4 v[0:3], v[36:37] offset:1888
	flat_load_dwordx4 v[4:7], v[36:37] offset:2016
	flat_load_dwordx4 v[8:11], v[28:29] offset:192
	flat_load_dwordx4 v[12:15], v[28:29] offset:208
	v_lshlrev_b32_e32 v22, 3, v33
	v_mad_i32_i24 v24, v66, s58, v44
	v_mad_i32_i24 v33, v56, s58, v47
	v_mad_i32_i24 v29, v57, s58, v48
	v_mul_u32_u24_e32 v25, 0x190, v66
	v_mad_i32_i24 v26, v67, s58, v45
	v_mul_u32_u24_e32 v27, 0x190, v67
	v_mul_u32_u24_e32 v45, 0x300, v67
	v_mul_u32_u24_e32 v39, 0x190, v57
	v_pk_mul_lo_u16 v42, v58, s37 op_sel_hi:[1,0]
	v_mad_i32_i24 v43, v69, s58, v49
	v_mad_i32_i24 v44, v59, s58, v52
	v_mad_i32_i24 v52, v71, s58, v53
	v_add3_u32 v53, v46, v65, v64
	v_lshlrev_b32_e32 v64, 4, v24
	v_lshlrev_b32_e32 v67, 4, v33
	v_lshlrev_b32_e32 v28, 3, v33
	v_lshlrev_b32_e32 v33, 4, v29
	v_mul_u32_u24_e32 v37, 0x190, v56
	v_mul_u32_u24_e32 v47, 0x300, v56
	v_mul_u32_u24_e32 v56, 0x300, v57
	v_mad_i32_i24 v38, v68, s58, v50
	v_mul_u32_u24_e32 v57, 0x300, v68
	v_pk_mul_lo_u16 v48, v60, s37 op_sel_hi:[1,0]
	v_mad_i32_i24 v49, v70, s58, v51
	v_mul_u32_u24_e32 v60, 0x300, v70
	v_mad_i32_i24 v50, v61, s58, v54
	v_mul_u32_u24_e32 v54, 0x300, v61
	v_mul_u32_u24_e32 v61, 0x300, v71
	v_and_b32_e32 v68, 0xfff0, v42
	v_lshrrev_b32_e32 v70, 16, v42
	v_lshlrev_b32_e32 v71, 4, v43
	v_lshlrev_b32_e32 v42, 3, v43
	v_add3_u32 v43, v46, v25, v64
	v_add3_u32 v64, v46, v39, v33
	v_mov_b32_e32 v33, v31
	v_pk_mul_f32 v[30:31], v[34:35], v[20:21] op_sel_hi:[1,0]
	v_pk_mul_f32 v[32:33], v[32:33], v[20:21] op_sel_hi:[1,0]
	v_ashrrev_i32_e32 v23, 31, v22
	v_mul_u32_u24_e32 v66, 0x300, v66
	v_lshlrev_b32_e32 v24, 3, v24
	v_ashrrev_i32_e32 v25, 31, v24
	v_lshlrev_b32_e32 v65, 4, v26
	v_and_b32_e32 v72, 0xfff0, v48
	v_lshrrev_b32_e32 v74, 16, v48
	v_lshlrev_b32_e32 v75, 4, v49
	v_lshlrev_b32_e32 v48, 3, v49
	v_add3_u32 v49, v46, v27, v65
	v_lshlrev_b32_e32 v26, 3, v26
	v_ashrrev_i32_e32 v27, 31, v26
	v_pk_mul_lo_u16 v51, v62, s37 op_sel_hi:[1,0]
	v_lshlrev_b32_e32 v36, 3, v29
	v_and_b32_e32 v76, 0xfff0, v51
	v_lshrrev_b32_e32 v78, 16, v51
	v_add3_u32 v51, v46, v37, v67
	v_ashrrev_i32_e32 v29, 31, v28
	v_ashrrev_i32_e32 v37, 31, v36
	v_mul_u32_u24_e32 v58, 0x300, v69
	v_lshlrev_b32_e32 v69, 4, v38
	v_add3_u32 v65, v46, v68, v69
	v_lshlrev_b32_e32 v38, 3, v38
	v_ashrrev_i32_e32 v39, 31, v38
	v_lshlrev_b32_e32 v73, 4, v44
	v_mul_u32_u24_e32 v59, 0x300, v59
	v_lshlrev_b32_e32 v44, 3, v44
	v_lshlrev_b32_e32 v77, 4, v50
	v_lshlrev_b32_e32 v50, 3, v50
	v_lshlrev_b32_e32 v79, 4, v52
	v_lshlrev_b32_e32 v52, 3, v52
	v_mul_u32_u24_e32 v62, 0x190, v63
	v_mul_u32_u24_e32 v63, 0x300, v63
	s_waitcnt vmcnt(0) lgkmcnt(0)
; DEV int opaque_tid() { int t = threadIdx.x; asm volatile("" : "+v"(t)); return t; }
; #define LDSP(T) __attribute__((address_space(3))) T*
; #define GLOAD(kt, buf) do { _Pragma("unroll") for (int i = 0; i < 4; ++i) glds16(Ap + (long)i * 64 * lda + (kt) * 64, As + (buf) * 32768 + soff + i * 8192); \
;     _Pragma("unroll") for (int i = 0; i < NB; ++i) glds16(Bp + (long)i * 64 * ldb + (kt) * 64, Bs + (buf) * 32768 + soff + i * 8192); } while (0)
; template <int NCH, int STRIDE> DEV void slab_flush(char* slab, u16* grow0, int gstride, int lane) {
;   asm volatile("s_waitcnt lgkmcnt(0)" ::: "memory");
; #pragma unroll
;   for (int i = 0; i < NCH / 2; ++i) {
;     const int q = i * 64 + lane, row = q / NCH, cc = q - row * NCH;
;     const u32x4 v = *(LDSP(const u32x4))(slab + row * STRIDE + cc * 16);
;     *reinterpret_cast<u32x4*>(grow0 + (long)row * gstride + cc * 8) = v;
;   }
;   asm volatile("s_waitcnt lgkmcnt(0)" ::: "memory");
; }
; template <int WM, int WN, int BN, int EPI>
; DEV void gemm_tile(const u16* __restrict__ A, int lda, const u16* __restrict__ Bt, int ldb, int K, int m0, char* lds,
;                    const Params& P, int layer, int batch, int nt) {
;     ...
;   const int tid = opaque_tid(), wid = tid >> 6, lane = tid & 63, r32 = lane & 31, hi = lane >> 5;
;   const int wm = wid / WN, wn = wid % WN;
;   char* As = lds; char* Bs = lds + 65536;
;   f32x16 acc[MI][NI];
; #pragma unroll
;   for (int mi = 0; mi < MI; ++mi)
; #pragma unroll
;     for (int ni = 0; ni < NI; ++ni) acc[mi][ni] = f32x16{};
;   const int srow = tid >> 3, sch = (tid & 7) ^ ((srow >> 1) & 7);
;   const u16* Ap = A + (long)(m0 + srow) * lda + sch * 8;
;   const u16* Bp = Bt + (long)srow * ldb + sch * 8;
;   const int soff = tid * 16;
;     ...
;   GLOAD(0, 0); asm volatile("s_waitcnt vmcnt(0)" ::: "memory"); __syncthreads();
	v_mov_b32_e32 v34, v0
	v_mov_b32_e32 v35, v4
	v_mov_b32_e32 v4, v1
	v_mov_b32_e32 v0, v2
	v_mov_b32_e32 v1, v6
	v_mov_b32_e32 v6, v3
	v_pk_mul_f32 v[2:3], v[16:17], v[34:35]
	v_pk_mul_f32 v[4:5], v[18:19], v[4:5]
	v_pk_mul_f32 v[0:1], v[30:31], v[0:1]
	v_pk_mul_f32 v[6:7], v[32:33], v[6:7]
	v_pk_mul_f32 v[16:17], v[2:3], v[8:9]
	v_pk_mul_f32 v[18:19], v[4:5], v[10:11]
	v_pk_mul_f32 v[30:31], v[0:1], v[12:13]
	v_pk_mul_f32 v[32:33], v[6:7], v[14:15]
	v_pk_mul_f32 v[2:3], v[2:3], v[8:9] op_sel:[1,0] op_sel_hi:[0,1]
	v_pk_mul_f32 v[4:5], v[4:5], v[10:11] op_sel:[1,0] op_sel_hi:[0,1]
	v_pk_mul_f32 v[0:1], v[0:1], v[12:13] op_sel:[1,0] op_sel_hi:[0,1]
	v_pk_mul_f32 v[6:7], v[6:7], v[14:15] op_sel:[1,0] op_sel_hi:[0,1]
	v_sub_f32_e32 v8, v16, v17
	v_sub_f32_e32 v9, v18, v19
	v_sub_f32_e32 v10, v30, v31
	v_sub_f32_e32 v11, v32, v33
	v_add_f32_e32 v2, v2, v3
	v_add_f32_e32 v3, v4, v5
	v_add_f32_e32 v4, v0, v1
	v_cvt_pk_bf16_f32 v0, v8, v9
	v_cvt_pk_bf16_f32 v1, v10, v11
	v_add_f32_e32 v5, v6, v7
	ds_write_b64 v21, v[0:1] offset:304
	v_cvt_pk_bf16_f32 v0, v2, v3
	v_cvt_pk_bf16_f32 v1, v4, v5
	ds_write_b64 v21, v[0:1] offset:368
	s_waitcnt lgkmcnt(0)
	ds_read_b128 v[0:3], v53
	v_lshl_add_u64 v[4:5], v[40:41], 0, v[184:185]
	v_lshl_add_u64 v[4:5], v[22:23], 1, v[4:5]
	v_lshlrev_b32_e32 v184, 1, v66
	v_add3_u32 v6, v46, v70, v71
	s_waitcnt lgkmcnt(0)
	flat_store_dwordx4 v[4:5], v[0:3]
	ds_read_b128 v[0:3], v43
	v_lshl_add_u64 v[4:5], v[40:41], 0, v[184:185]
	v_lshl_add_u64 v[4:5], v[24:25], 1, v[4:5]
	v_lshlrev_b32_e32 v184, 1, v45
	v_ashrrev_i32_e32 v43, 31, v42
	s_waitcnt lgkmcnt(0)
	flat_store_dwordx4 v[4:5], v[0:3]
	ds_read_b128 v[0:3], v49
	v_lshl_add_u64 v[4:5], v[40:41], 0, v[184:185]
	v_lshl_add_u64 v[4:5], v[26:27], 1, v[4:5]
	v_lshlrev_b32_e32 v184, 1, v47
	v_add3_u32 v7, v46, v72, v73
	s_waitcnt lgkmcnt(0)
	flat_store_dwordx4 v[4:5], v[0:3]
	ds_read_b128 v[0:3], v51
	v_lshl_add_u64 v[4:5], v[40:41], 0, v[184:185]
	v_lshl_add_u64 v[4:5], v[28:29], 1, v[4:5]
	v_lshlrev_b32_e32 v184, 1, v56
	v_ashrrev_i32_e32 v45, 31, v44
	s_waitcnt lgkmcnt(0)
	flat_store_dwordx4 v[4:5], v[0:3]
	ds_read_b128 v[0:3], v64
	v_lshl_add_u64 v[4:5], v[40:41], 0, v[184:185]
	v_lshl_add_u64 v[4:5], v[36:37], 1, v[4:5]
	v_lshlrev_b32_e32 v184, 1, v57
	v_add3_u32 v8, v46, v74, v75
	s_waitcnt lgkmcnt(0)
	flat_store_dwordx4 v[4:5], v[0:3]
	ds_read_b128 v[0:3], v65
	v_lshl_add_u64 v[4:5], v[40:41], 0, v[184:185]
	v_lshl_add_u64 v[4:5], v[38:39], 1, v[4:5]
	v_lshlrev_b32_e32 v184, 1, v58
	v_ashrrev_i32_e32 v49, 31, v48
	s_waitcnt lgkmcnt(0)
	flat_store_dwordx4 v[4:5], v[0:3]
	ds_read_b128 v[0:3], v6
	v_lshl_add_u64 v[4:5], v[40:41], 0, v[184:185]
	v_lshl_add_u64 v[4:5], v[42:43], 1, v[4:5]
	v_lshlrev_b32_e32 v184, 1, v59
	v_add3_u32 v6, v46, v76, v77
	s_waitcnt lgkmcnt(0)
	flat_store_dwordx4 v[4:5], v[0:3]
	ds_read_b128 v[0:3], v7
	v_lshl_add_u64 v[4:5], v[40:41], 0, v[184:185]
	v_lshl_add_u64 v[4:5], v[44:45], 1, v[4:5]
	v_lshlrev_b32_e32 v184, 1, v60
	v_ashrrev_i32_e32 v51, 31, v50
	s_waitcnt lgkmcnt(0)
	flat_store_dwordx4 v[4:5], v[0:3]
	ds_read_b128 v[0:3], v8
	v_lshl_add_u64 v[4:5], v[40:41], 0, v[184:185]
	v_lshl_add_u64 v[4:5], v[48:49], 1, v[4:5]
	v_lshlrev_b32_e32 v184, 1, v54
	v_add3_u32 v7, v46, v78, v79
	s_waitcnt lgkmcnt(0)
	flat_store_dwordx4 v[4:5], v[0:3]
	ds_read_b128 v[0:3], v6
	v_lshl_add_u64 v[4:5], v[40:41], 0, v[184:185]
	v_lshl_add_u64 v[4:5], v[50:51], 1, v[4:5]
	v_lshlrev_b32_e32 v184, 1, v61
	v_ashrrev_i32_e32 v53, 31, v52
	s_waitcnt lgkmcnt(0)
	flat_store_dwordx4 v[4:5], v[0:3]
	ds_read_b128 v[0:3], v7
	v_lshl_add_u64 v[4:5], v[40:41], 0, v[184:185]
	v_lshl_add_u64 v[4:5], v[52:53], 1, v[4:5]
	v_add3_u32 v6, v46, v62, v80
	v_lshlrev_b32_e32 v184, 1, v63
	s_waitcnt lgkmcnt(0)
	flat_store_dwordx4 v[4:5], v[0:3]
	ds_read_b128 v[0:3], v6
	v_lshlrev_b32_e32 v6, 3, v55
	v_lshl_add_u64 v[4:5], v[40:41], 0, v[184:185]
	v_ashrrev_i32_e32 v7, 31, v6
	v_lshl_add_u64 v[4:5], v[6:7], 1, v[4:5]
	s_waitcnt lgkmcnt(0)
	flat_store_dwordx4 v[4:5], v[0:3]
	s_waitcnt lgkmcnt(0)
	s_waitcnt lgkmcnt(0)
	s_barrier
	s_cbranch_execnz .LBB0_355
.LBB0_359:
	s_lshl_b32 s2, s54, 16
	s_or_b32 s2, s2, s53
	s_add_u32 s60, s48, s2
	v_mov_b32_e32 v152, v226
	s_addc_u32 s61, s52, 0
	s_lshl_b32 s2, s55, 8
	s_mov_b64 s[62:63], 0xc000
	v_ashrrev_i32_e32 v0, 3, v152
	v_lshrrev_b32_e32 v1, 4, v152
	v_xor_b32_e32 v1, v1, v152
	v_add_u32_e32 v2, s2, v0
	v_ashrrev_i32_e32 v3, 31, v2
	v_lshlrev_b32_e32 v1, 4, v1
	v_lshlrev_b32_e32 v156, 4, v152
	v_lshlrev_b64 v[2:3], 8, v[2:3]
	v_and_b32_e32 v184, 0x70, v1
	v_ashrrev_i32_e32 v1, 31, v0
	v_add_u32_e32 v148, 0, v156
	v_lshl_add_u64 v[2:3], s[16:17], 0, v[2:3]
	v_lshlrev_b64 v[0:1], 8, v[0:1]
	v_readfirstlane_b32 s3, v148
	v_add_u32_e32 v5, 0x2000, v148
	v_lshl_add_u64 v[128:129], v[2:3], 0, v[184:185]
	v_lshl_add_u64 v[0:1], s[60:61], 0, v[0:1]
	s_mov_b32 m0, s3
	s_mov_b64 s[60:61], 0x4000
	v_readfirstlane_b32 s3, v5
	v_add_u32_e32 v5, 0x4000, v148
	global_load_lds_dwordx4 v[128:129], off
	v_lshl_add_u64 v[2:3], v[128:129], 0, s[60:61]
	s_mov_b32 m0, s3
	v_readfirstlane_b32 s3, v5
	v_add_u32_e32 v5, 0x6000, v148
	global_load_lds_dwordx4 v[2:3], off
	v_lshl_add_u64 v[2:3], v[128:129], 0, s[40:41]
	s_mov_b32 m0, s3
	v_readfirstlane_b32 s3, v5
	global_load_lds_dwordx4 v[2:3], off
	v_lshl_add_u64 v[2:3], v[128:129], 0, s[62:63]
	s_mov_b32 m0, s3
	s_add_i32 s3, 0, 0x10000
	global_load_lds_dwordx4 v[2:3], off
	v_add_u32_e32 v2, s3, v156
	v_add_u32_e32 v3, 0x2000, v2
	v_readfirstlane_b32 s22, v2
	v_lshl_add_u64 v[130:131], v[0:1], 0, v[184:185]
	s_mov_b32 m0, s22
	v_readfirstlane_b32 s22, v3
	v_add_u32_e32 v3, 0x4000, v2
	global_load_lds_dwordx4 v[130:131], off
	v_lshl_add_u64 v[0:1], v[130:131], 0, s[60:61]
	s_mov_b32 m0, s22
	v_readfirstlane_b32 s22, v3
	v_add_u32_e32 v2, 0x6000, v2
	global_load_lds_dwordx4 v[0:1], off
	v_lshl_add_u64 v[0:1], v[130:131], 0, s[40:41]
	s_mov_b32 m0, s22
	v_readfirstlane_b32 s22, v2
	v_and_b32_e32 v154, 31, v152
	global_load_lds_dwordx4 v[0:1], off
	v_lshl_add_u64 v[0:1], v[130:131], 0, s[62:63]
	s_mov_b32 m0, s22
	v_add_u32_e32 v5, 0x8000, v148
	global_load_lds_dwordx4 v[0:1], off
	v_lshlrev_b32_e32 v1, 7, v154
	v_add_u32_e32 v153, s3, v1
	s_add_i32 s3, 0, 0x18000
	v_ashrrev_i32_e32 v149, 6, v152
	v_add_u32_e32 v157, s3, v156
	v_readfirstlane_b32 s3, v5
	v_lshlrev_b32_e32 v0, 12, v149
	v_lshl_add_u64 v[2:3], v[128:129], 0, s[30:31]
	s_mov_b32 m0, s3
	v_readfirstlane_b32 s3, v157
	s_waitcnt vmcnt(0)
	s_waitcnt vmcnt(0) lgkmcnt(0)
	s_barrier
; #define SBAR() __builtin_amdgcn_sched_barrier(0)
; DEV void glds16(const u16* g, char* l) { __builtin_amdgcn_global_load_lds((const unsigned*)g, (unsigned*)l, 16, 0, 0); }
; template <int WM, int WN, int BN, int EPI>
; DEV void gemm_tile(const u16* __restrict__ A, int lda, const u16* __restrict__ Bt, int ldb, int K, int m0, char* lds,
;                    const Params& P, int layer, int batch, int nt) {
;     ...
;   for (int kt = 0; kt < nk; ++kt) {
;     const bool more = kt + 1 < nk;
;     const int nb = (kt + 1) & 1;
;     const char* as = As + (kt & 1) * 32768; const char* bs = Bs + (kt & 1) * 32768;
; #pragma unroll
;     for (int ks = 0; ks < 4; ++ks) {
;       if (more) { glds16(Ap + (long)ks * 64 * lda + (kt + 1) * 64, As + nb * 32768 + soff + ks * 8192);
;                   if (ks < NB) glds16(Bp + (long)ks * 64 * ldb + (kt + 1) * 64, Bs + nb * 32768 + soff + ks * 8192); }
;       SBAR();
;       bf16x8 xf[MI], wf[NI];
; #pragma unroll
;       for (int mi = 0; mi < MI; ++mi) xf[mi] = *reinterpret_cast<const bf16x8*>(as + swz128(wm * (MI * 32) + mi * 32 + r32, ks * 2 + hi));
; #pragma unroll
;       for (int ni = 0; ni < NI; ++ni) wf[ni] = *reinterpret_cast<const bf16x8*>(bs + swz128(wn * (NI * 32) + ni * 32 + r32, ks * 2 + hi));
; #pragma unroll
;       for (int mi = 0; mi < MI; ++mi)
; #pragma unroll
;         for (int ni = 0; ni < NI; ++ni) acc[mi][ni] = __builtin_amdgcn_mfma_f32_32x32x16_bf16(wf[ni], xf[mi], acc[mi][ni], 0, 0, 0);
;     }
;     asm volatile("s_waitcnt vmcnt(0)" ::: "memory");
;     __syncthreads();
;   }
	v_add3_u32 v151, 0, v0, v1
	v_lshl_add_u64 v[0:1], v[130:131], 0, s[30:31]
	global_load_lds_dwordx4 v[2:3], off
	s_mov_b32 m0, s3
	v_lshrrev_b32_e32 v4, 5, v152
	global_load_lds_dwordx4 v[0:1], off
	v_bfe_u32 v155, v152, 5, 1
	v_bfe_u32 v150, v152, 1, 3
	v_bitop3_b32 v0, v4, v150, 1 bitop3:0x6c
	v_lshlrev_b32_e32 v4, 4, v0
	v_add_u32_e32 v158, v153, v4
	ds_read_b128 v[0:3], v158
	v_add_u32_e32 v159, v151, v4
	ds_read_b128 v[64:67], v159
	v_add_u32_e32 v133, 0xa000, v148
	s_mov_b64 s[60:61], 0x4080
	v_add_u32_e32 v132, 0x2000, v157
	v_readfirstlane_b32 s3, v133
	v_lshl_add_u64 v[78:79], v[128:129], 0, s[60:61]
	s_mov_b32 m0, s3
	s_waitcnt lgkmcnt(0)
	v_mfma_f32_32x32x16_bf16 v[48:63], v[0:3], v[64:67], 0
	ds_read_b128 v[0:3], v158 offset:4096
	ds_read_b128 v[4:7], v158 offset:8192
	v_readfirstlane_b32 s3, v132
	v_lshl_add_u64 v[76:77], v[130:131], 0, s[60:61]
	s_waitcnt lgkmcnt(0)
	v_mfma_f32_32x32x16_bf16 v[32:47], v[0:3], v[64:67], 0
	ds_read_b128 v[0:3], v158 offset:12288
	ds_read_b128 v[68:71], v158 offset:16384
	s_waitcnt lgkmcnt(0)
	v_mfma_f32_32x32x16_bf16 v[112:127], v[68:71], v[64:67], 0
	ds_read_b128 v[68:71], v158 offset:20480
	ds_read_b128 v[72:75], v158 offset:24576
	s_waitcnt lgkmcnt(0)
	v_mfma_f32_32x32x16_bf16 v[96:111], v[68:71], v[64:67], 0
	ds_read_b128 v[68:71], v158 offset:28672
	global_load_lds_dwordx4 v[78:79], off
	s_mov_b32 m0, s3
	s_nop 0
	global_load_lds_dwordx4 v[76:77], off
	v_mfma_f32_32x32x16_bf16 v[16:31], v[4:7], v[64:67], 0
	v_mfma_f32_32x32x16_bf16 v[0:15], v[0:3], v[64:67], 0
	v_mfma_f32_32x32x16_bf16 v[80:95], v[72:75], v[64:67], 0
	s_waitcnt lgkmcnt(0)
	v_mfma_f32_32x32x16_bf16 v[64:79], v[68:71], v[64:67], 0
	v_bitop3_b32 v132, v155, v150, 2 bitop3:0x36
	v_lshlrev_b32_e32 v136, 4, v132
	v_add_u32_e32 v160, v153, v136
	ds_read_b128 v[132:135], v160
	v_add_u32_e32 v161, v151, v136
	ds_read_b128 v[136:139], v161
	v_add_u32_e32 v163, 0xc000, v148
	v_add_u32_e32 v162, 0x4000, v157
	v_readfirstlane_b32 s3, v163
	v_lshl_add_u64 v[146:147], v[128:129], 0, s[42:43]
	s_mov_b32 m0, s3
	v_readfirstlane_b32 s3, v162
	s_waitcnt lgkmcnt(0)
	v_mfma_f32_32x32x16_bf16 v[48:63], v[132:135], v[136:139], v[48:63]
	ds_read_b128 v[132:135], v160 offset:4096
	ds_read_b128 v[140:143], v160 offset:8192
	v_lshl_add_u64 v[144:145], v[130:131], 0, s[42:43]
	s_waitcnt lgkmcnt(0)
	v_mfma_f32_32x32x16_bf16 v[32:47], v[132:135], v[136:139], v[32:47]
	v_mfma_f32_32x32x16_bf16 v[16:31], v[140:143], v[136:139], v[16:31]
	ds_read_b128 v[132:135], v160 offset:12288
	ds_read_b128 v[140:143], v160 offset:16384
	s_waitcnt lgkmcnt(0)
	v_mfma_f32_32x32x16_bf16 v[0:15], v[132:135], v[136:139], v[0:15]
	v_mfma_f32_32x32x16_bf16 v[112:127], v[140:143], v[136:139], v[112:127]
	ds_read_b128 v[132:135], v160 offset:20480
	ds_read_b128 v[140:143], v160 offset:24576
	s_waitcnt lgkmcnt(0)
	v_mfma_f32_32x32x16_bf16 v[96:111], v[132:135], v[136:139], v[96:111]
	ds_read_b128 v[132:135], v160 offset:28672
	global_load_lds_dwordx4 v[146:147], off
	s_mov_b32 m0, s3
	s_nop 0
	global_load_lds_dwordx4 v[144:145], off
	v_mfma_f32_32x32x16_bf16 v[80:95], v[140:143], v[136:139], v[80:95]
	s_waitcnt lgkmcnt(0)
	v_mfma_f32_32x32x16_bf16 v[64:79], v[132:135], v[136:139], v[64:79]
	v_bitop3_b32 v132, v155, v150, 4 bitop3:0x36
	v_lshlrev_b32_e32 v136, 4, v132
	v_add_u32_e32 v144, v153, v136
	ds_read_b128 v[132:135], v144
	v_add_u32_e32 v145, v151, v136
	ds_read_b128 v[136:139], v145
	v_add_u32_e32 v147, 0xe000, v148
	s_mov_b64 s[60:61], 0xc080
	v_add_u32_e32 v146, 0x6000, v157
	v_readfirstlane_b32 s3, v147
	v_lshl_add_u64 v[128:129], v[128:129], 0, s[60:61]
	s_mov_b32 m0, s3
	s_waitcnt lgkmcnt(0)
	v_mfma_f32_32x32x16_bf16 v[48:63], v[132:135], v[136:139], v[48:63]
	ds_read_b128 v[132:135], v144 offset:4096
	ds_read_b128 v[140:143], v144 offset:8192
	v_readfirstlane_b32 s3, v146
	v_lshl_add_u64 v[130:131], v[130:131], 0, s[60:61]
	s_waitcnt lgkmcnt(0)
	v_mfma_f32_32x32x16_bf16 v[32:47], v[132:135], v[136:139], v[32:47]
	v_mfma_f32_32x32x16_bf16 v[16:31], v[140:143], v[136:139], v[16:31]
	ds_read_b128 v[132:135], v144 offset:12288
	ds_read_b128 v[140:143], v144 offset:16384
	s_waitcnt lgkmcnt(0)
	v_mfma_f32_32x32x16_bf16 v[0:15], v[132:135], v[136:139], v[0:15]
	v_mfma_f32_32x32x16_bf16 v[112:127], v[140:143], v[136:139], v[112:127]
	ds_read_b128 v[132:135], v144 offset:20480
	ds_read_b128 v[140:143], v144 offset:24576
	s_waitcnt lgkmcnt(0)
	v_mfma_f32_32x32x16_bf16 v[96:111], v[132:135], v[136:139], v[96:111]
	ds_read_b128 v[132:135], v144 offset:28672
	global_load_lds_dwordx4 v[128:129], off
	s_mov_b32 m0, s3
	s_nop 0
	global_load_lds_dwordx4 v[130:131], off
	v_mfma_f32_32x32x16_bf16 v[80:95], v[140:143], v[136:139], v[80:95]
	s_waitcnt lgkmcnt(0)
	v_mfma_f32_32x32x16_bf16 v[64:79], v[132:135], v[136:139], v[64:79]
	v_bitop3_b32 v128, v155, v150, 6 bitop3:0x36
	v_lshlrev_b32_e32 v132, 4, v128
	v_add_u32_e32 v148, v153, v132
	ds_read_b128 v[128:131], v148
	v_add_u32_e32 v140, v151, v132
	ds_read_b128 v[132:135], v140
	s_waitcnt lgkmcnt(0)
	v_mfma_f32_32x32x16_bf16 v[48:63], v[128:131], v[132:135], v[48:63]
	ds_read_b128 v[128:131], v148 offset:4096
	s_waitcnt lgkmcnt(0)
	v_mfma_f32_32x32x16_bf16 v[32:47], v[128:131], v[132:135], v[32:47]
	ds_read_b128 v[128:131], v148 offset:8192
	s_waitcnt lgkmcnt(0)
	v_mfma_f32_32x32x16_bf16 v[16:31], v[128:131], v[132:135], v[16:31]
	ds_read_b128 v[128:131], v148 offset:12288
	s_waitcnt lgkmcnt(0)
	v_mfma_f32_32x32x16_bf16 v[0:15], v[128:131], v[132:135], v[0:15]
	ds_read_b128 v[128:131], v148 offset:16384
	s_waitcnt lgkmcnt(0)
	v_mfma_f32_32x32x16_bf16 v[112:127], v[128:131], v[132:135], v[112:127]
	ds_read_b128 v[128:131], v148 offset:20480
	s_waitcnt lgkmcnt(0)
	v_mfma_f32_32x32x16_bf16 v[96:111], v[128:131], v[132:135], v[96:111]
	ds_read_b128 v[128:131], v148 offset:24576
	s_waitcnt lgkmcnt(0)
	v_mfma_f32_32x32x16_bf16 v[80:95], v[128:131], v[132:135], v[80:95]
	ds_read_b128 v[128:131], v148 offset:28672
	s_waitcnt vmcnt(0)
	s_waitcnt vmcnt(0) lgkmcnt(0)
	s_barrier
; #define SBAR() __builtin_amdgcn_sched_barrier(0)
;   DEV float* ssq_ckv() const { return (float*)(b + O_SSQCKV); }
; DEV void glds16(const u16* g, char* l) { __builtin_amdgcn_global_load_lds((const unsigned*)g, (unsigned*)l, 16, 0, 0); }
; DEV void epi_ukv(f32x16 (&acc)[1][8], const Params& P, int layer, int batch, int m0, int head, int wid, int r32, int hi, char* lds) {
;   const int t = m0 + wid * 32 + r32;
;   const float rc = __builtin_amdgcn_rsqf((WS{P.ws}.ssq_ckv()[t] + WS{P.ws}.ssq_ckv()[TB + t]) * (1.f / 128.f) + EPS);
; template <int WM, int WN, int BN, int EPI>
; DEV void gemm_tile(const u16* __restrict__ A, int lda, const u16* __restrict__ Bt, int ldb, int K, int m0, char* lds,
;                    const Params& P, int layer, int batch, int nt) {
;     ...
;   for (int kt = 0; kt < nk; ++kt) {
;     const bool more = kt + 1 < nk;
;     const int nb = (kt + 1) & 1;
;     const char* as = As + (kt & 1) * 32768; const char* bs = Bs + (kt & 1) * 32768;
; #pragma unroll
;     for (int ks = 0; ks < 4; ++ks) {
;       if (more) { glds16(Ap + (long)ks * 64 * lda + (kt + 1) * 64, As + nb * 32768 + soff + ks * 8192);
;                   if (ks < NB) glds16(Bp + (long)ks * 64 * ldb + (kt + 1) * 64, Bs + nb * 32768 + soff + ks * 8192); }
;       SBAR();
;       bf16x8 xf[MI], wf[NI];
; #pragma unroll
;       for (int mi = 0; mi < MI; ++mi) xf[mi] = *reinterpret_cast<const bf16x8*>(as + swz128(wm * (MI * 32) + mi * 32 + r32, ks * 2 + hi));
; #pragma unroll
;       for (int ni = 0; ni < NI; ++ni) wf[ni] = *reinterpret_cast<const bf16x8*>(bs + swz128(wn * (NI * 32) + ni * 32 + r32, ks * 2 + hi));
; #pragma unroll
;       for (int mi = 0; mi < MI; ++mi)
; #pragma unroll
;         for (int ni = 0; ni < NI; ++ni) acc[mi][ni] = __builtin_amdgcn_mfma_f32_32x32x16_bf16(wf[ni], xf[mi], acc[mi][ni], 0, 0, 0);
;     }
;     asm volatile("s_waitcnt vmcnt(0)" ::: "memory");
;     __syncthreads();
;   }
	v_mfma_f32_32x32x16_bf16 v[64:79], v[128:131], v[132:135], v[64:79]
	ds_read_b128 v[128:131], v158 offset:32768
	ds_read_b128 v[132:135], v159 offset:32768
	s_waitcnt lgkmcnt(0)
	v_mfma_f32_32x32x16_bf16 v[48:63], v[128:131], v[132:135], v[48:63]
	ds_read_b128 v[128:131], v158 offset:36864
	s_waitcnt lgkmcnt(0)
	v_mfma_f32_32x32x16_bf16 v[32:47], v[128:131], v[132:135], v[32:47]
	ds_read_b128 v[128:131], v158 offset:40960
	s_waitcnt lgkmcnt(0)
	v_mfma_f32_32x32x16_bf16 v[16:31], v[128:131], v[132:135], v[16:31]
	ds_read_b128 v[128:131], v158 offset:45056
	s_waitcnt lgkmcnt(0)
	v_mfma_f32_32x32x16_bf16 v[0:15], v[128:131], v[132:135], v[0:15]
	ds_read_b128 v[128:131], v158 offset:49152
	s_waitcnt lgkmcnt(0)
	v_mfma_f32_32x32x16_bf16 v[112:127], v[128:131], v[132:135], v[112:127]
	ds_read_b128 v[128:131], v158 offset:53248
	s_waitcnt lgkmcnt(0)
	v_mfma_f32_32x32x16_bf16 v[96:111], v[128:131], v[132:135], v[96:111]
	ds_read_b128 v[128:131], v158 offset:57344
	s_waitcnt lgkmcnt(0)
	v_mfma_f32_32x32x16_bf16 v[80:95], v[128:131], v[132:135], v[80:95]
	ds_read_b128 v[128:131], v158 offset:61440
	s_waitcnt lgkmcnt(0)
	v_mfma_f32_32x32x16_bf16 v[64:79], v[128:131], v[132:135], v[64:79]
	ds_read_b128 v[128:131], v160 offset:32768
	ds_read_b128 v[132:135], v161 offset:32768
	s_waitcnt lgkmcnt(0)
	v_mfma_f32_32x32x16_bf16 v[48:63], v[128:131], v[132:135], v[48:63]
	ds_read_b128 v[128:131], v160 offset:36864
	s_waitcnt lgkmcnt(0)
	v_mfma_f32_32x32x16_bf16 v[32:47], v[128:131], v[132:135], v[32:47]
	ds_read_b128 v[128:131], v160 offset:40960
	s_waitcnt lgkmcnt(0)
	v_mfma_f32_32x32x16_bf16 v[16:31], v[128:131], v[132:135], v[16:31]
	ds_read_b128 v[128:131], v160 offset:45056
	s_waitcnt lgkmcnt(0)
	v_mfma_f32_32x32x16_bf16 v[0:15], v[128:131], v[132:135], v[0:15]
	ds_read_b128 v[128:131], v160 offset:49152
	s_waitcnt lgkmcnt(0)
	v_mfma_f32_32x32x16_bf16 v[112:127], v[128:131], v[132:135], v[112:127]
	ds_read_b128 v[128:131], v160 offset:53248
	s_waitcnt lgkmcnt(0)
	v_mfma_f32_32x32x16_bf16 v[96:111], v[128:131], v[132:135], v[96:111]
	ds_read_b128 v[128:131], v160 offset:57344
	s_waitcnt lgkmcnt(0)
	v_mfma_f32_32x32x16_bf16 v[80:95], v[128:131], v[132:135], v[80:95]
	ds_read_b128 v[128:131], v160 offset:61440
	s_waitcnt lgkmcnt(0)
	v_mfma_f32_32x32x16_bf16 v[64:79], v[128:131], v[132:135], v[64:79]
	ds_read_b128 v[128:131], v144 offset:32768
	ds_read_b128 v[132:135], v145 offset:32768
	s_waitcnt lgkmcnt(0)
	v_mfma_f32_32x32x16_bf16 v[48:63], v[128:131], v[132:135], v[48:63]
	ds_read_b128 v[128:131], v144 offset:36864
	s_waitcnt lgkmcnt(0)
	v_mfma_f32_32x32x16_bf16 v[32:47], v[128:131], v[132:135], v[32:47]
	ds_read_b128 v[128:131], v144 offset:40960
	s_waitcnt lgkmcnt(0)
	v_mfma_f32_32x32x16_bf16 v[16:31], v[128:131], v[132:135], v[16:31]
	ds_read_b128 v[128:131], v144 offset:45056
	s_waitcnt lgkmcnt(0)
	v_mfma_f32_32x32x16_bf16 v[0:15], v[128:131], v[132:135], v[0:15]
	ds_read_b128 v[128:131], v144 offset:49152
	s_waitcnt lgkmcnt(0)
	v_mfma_f32_32x32x16_bf16 v[112:127], v[128:131], v[132:135], v[112:127]
	ds_read_b128 v[128:131], v144 offset:53248
	s_waitcnt lgkmcnt(0)
	v_mfma_f32_32x32x16_bf16 v[96:111], v[128:131], v[132:135], v[96:111]
	ds_read_b128 v[128:131], v144 offset:57344
	s_waitcnt lgkmcnt(0)
	v_mfma_f32_32x32x16_bf16 v[80:95], v[128:131], v[132:135], v[80:95]
	ds_read_b128 v[128:131], v144 offset:61440
	s_waitcnt lgkmcnt(0)
	v_mfma_f32_32x32x16_bf16 v[64:79], v[128:131], v[132:135], v[64:79]
	ds_read_b128 v[136:139], v148 offset:49152
	ds_read_b128 v[128:131], v140 offset:32768
	ds_read_b128 v[132:135], v148 offset:45056
	ds_read_b128 v[140:143], v148 offset:32768
	ds_read_b128 v[158:161], v148 offset:53248
	v_lshlrev_b32_e32 v157, 3, v155
	s_waitcnt lgkmcnt(3)
	v_mfma_f32_32x32x16_bf16 v[112:127], v[136:139], v[128:131], v[112:127]
	ds_read_b128 v[144:147], v148 offset:36864
	ds_read_b128 v[136:139], v148 offset:40960
	ds_read_b128 v[162:165], v148 offset:57344
	ds_read_b128 v[166:169], v148 offset:61440
	v_lshl_add_u32 v148, v149, 5, s2
	v_or_b32_e32 v150, v148, v154
	v_ashrrev_i32_e32 v151, 31, v150
	s_waitcnt vmcnt(0)
	s_waitcnt lgkmcnt(0)
	s_barrier
	v_mfma_f32_32x32x16_bf16 v[96:111], v[158:161], v[128:131], v[96:111]
	v_lshl_add_u64 v[158:159], v[150:151], 2, s[18:19]
	v_add_co_u32_e32 v160, vcc, s93, v158
	s_nop 1
	v_addc_co_u32_e32 v161, vcc, 0, v159, vcc
	flat_load_dword v153, v[158:159]
	s_nop 0
	flat_load_dword v158, v[160:161]
	v_mfma_f32_32x32x16_bf16 v[80:95], v[162:165], v[128:131], v[80:95]
	v_mul_lo_u32 v149, v149, s99
	v_mul_u32_u24_e32 v159, 0x110, v154
	v_and_b32_e32 v184, 0xf0, v156
	s_lshl_b32 s22, s54, 8
	s_movk_i32 s2, 0xfff
	s_waitcnt vmcnt(0) lgkmcnt(0)
;   DEV u16* VB() const { return (u16*)(b + O_VB); }
;   DEV float* ssq_ckv() const { return (float*)(b + O_SSQCKV); }
; #define LDSP(T) __attribute__((address_space(3))) T*
; template <int NCH, int STRIDE> DEV void slab_flush(char* slab, u16* grow0, int gstride, int lane) {
;   asm volatile("s_waitcnt lgkmcnt(0)" ::: "memory");
; #pragma unroll
;   for (int i = 0; i < NCH / 2; ++i) {
;     const int q = i * 64 + lane, row = q / NCH, cc = q - row * NCH;
;     const u32x4 v = *(LDSP(const u32x4))(slab + row * STRIDE + cc * 16);
;     *reinterpret_cast<u32x4*>(grow0 + (long)row * gstride + cc * 8) = v;
;   }
;   asm volatile("s_waitcnt lgkmcnt(0)" ::: "memory");
; }
; DEV void epi_ukv(f32x16 (&acc)[1][8], const Params& P, int layer, int batch, int m0, int head, int wid, int r32, int hi, char* lds) {
;     ...
;   const float rc = __builtin_amdgcn_rsqf((WS{P.ws}.ssq_ckv()[t] + WS{P.ws}.ssq_ckv()[TB + t]) * (1.f / 128.f) + EPS);
;   char* slab = lds + wid * 12800; char* vdst = slab + r32 * 272;
; #pragma unroll
;   for (int ni = 4; ni < 8; ++ni)
; #pragma unroll
;     for (int r4 = 0; r4 < 4; ++r4) {
;       const f32x16& a = acc[0][ni];
;       st4lds(vdst, (ni - 4) * 32 + r4 * 8 + hi * 4, a[r4 * 4] * rc, a[r4 * 4 + 1] * rc, a[r4 * 4 + 2] * rc, a[r4 * 4 + 3] * rc);
;     }
;   slab_flush<16, 272>(slab, WS{P.ws}.VB() + (long)(m0 + wid * 32) * 512 + head * 128, 512, hi * 32 + r32);
	v_add_f32_e32 v153, v153, v158
	v_fmamk_f32 v153, v153, 0x3c000000, v227
	v_rsq_f32_e32 v158, v153
	v_add_u32_e32 v153, 0, v149
	v_add3_u32 v149, v153, v159, v157
	v_mfma_f32_32x32x16_bf16 v[64:79], v[166:169], v[128:131], v[64:79]
	v_mul_f32_e32 v112, v112, v158
	v_mul_f32_e32 v113, v113, v158
	v_mul_f32_e32 v114, v114, v158
	v_mul_f32_e32 v115, v115, v158
	v_mul_f32_e32 v159, v80, v158
	v_mul_f32_e32 v160, v81, v158
	v_cvt_pk_bf16_f32 v80, v112, v113
	v_cvt_pk_bf16_f32 v81, v114, v115
	v_mul_f32_e32 v116, v116, v158
	v_mul_f32_e32 v117, v117, v158
	v_mul_f32_e32 v118, v118, v158
	v_mul_f32_e32 v119, v119, v158
	ds_write_b64 v149, v[80:81]
	v_cvt_pk_bf16_f32 v80, v116, v117
	v_cvt_pk_bf16_f32 v81, v118, v119
	v_mul_f32_e32 v120, v120, v158
	v_mul_f32_e32 v121, v121, v158
	v_mul_f32_e32 v122, v122, v158
	v_mul_f32_e32 v123, v123, v158
	ds_write_b64 v149, v[80:81] offset:16
	v_cvt_pk_bf16_f32 v80, v120, v121
	v_cvt_pk_bf16_f32 v81, v122, v123
	v_mul_f32_e32 v124, v124, v158
	v_mul_f32_e32 v125, v125, v158
	v_mul_f32_e32 v126, v126, v158
	v_mul_f32_e32 v127, v127, v158
	ds_write_b64 v149, v[80:81] offset:32
	v_cvt_pk_bf16_f32 v80, v124, v125
	v_cvt_pk_bf16_f32 v81, v126, v127
	v_mul_f32_e32 v96, v96, v158
	v_mul_f32_e32 v97, v97, v158
	v_mul_f32_e32 v98, v98, v158
	v_mul_f32_e32 v99, v99, v158
	ds_write_b64 v149, v[80:81] offset:48
	v_cvt_pk_bf16_f32 v80, v96, v97
	v_cvt_pk_bf16_f32 v81, v98, v99
	v_mul_f32_e32 v100, v100, v158
	v_mul_f32_e32 v101, v101, v158
	v_mul_f32_e32 v102, v102, v158
	v_mul_f32_e32 v103, v103, v158
	ds_write_b64 v149, v[80:81] offset:64
	v_cvt_pk_bf16_f32 v80, v100, v101
	v_cvt_pk_bf16_f32 v81, v102, v103
	v_mul_f32_e32 v104, v104, v158
	v_mul_f32_e32 v105, v105, v158
	v_mul_f32_e32 v106, v106, v158
	v_mul_f32_e32 v107, v107, v158
	ds_write_b64 v149, v[80:81] offset:80
	v_cvt_pk_bf16_f32 v80, v104, v105
	v_cvt_pk_bf16_f32 v81, v106, v107
	v_mul_f32_e32 v108, v108, v158
	v_mul_f32_e32 v109, v109, v158
	v_mul_f32_e32 v110, v110, v158
	v_mul_f32_e32 v111, v111, v158
	ds_write_b64 v149, v[80:81] offset:96
	v_cvt_pk_bf16_f32 v80, v108, v109
	v_cvt_pk_bf16_f32 v81, v110, v111
	v_mul_f32_e32 v82, v82, v158
	v_mul_f32_e32 v83, v83, v158
	ds_write_b64 v149, v[80:81] offset:112
	v_cvt_pk_bf16_f32 v80, v159, v160
	v_cvt_pk_bf16_f32 v81, v82, v83
	v_mul_f32_e32 v84, v84, v158
	v_mul_f32_e32 v85, v85, v158
	v_mul_f32_e32 v86, v86, v158
	v_mul_f32_e32 v87, v87, v158
	ds_write_b64 v149, v[80:81] offset:128
	v_cvt_pk_bf16_f32 v80, v84, v85
	v_cvt_pk_bf16_f32 v81, v86, v87
	ds_write_b64 v149, v[80:81] offset:144
	v_mul_f32_e32 v80, v88, v158
	v_mul_f32_e32 v81, v89, v158
	v_mul_f32_e32 v82, v90, v158
	v_mul_f32_e32 v83, v91, v158
	v_cvt_pk_bf16_f32 v80, v80, v81
	v_cvt_pk_bf16_f32 v81, v82, v83
	ds_write_b64 v149, v[80:81] offset:160
	v_mul_f32_e32 v80, v92, v158
	v_mul_f32_e32 v81, v93, v158
	v_mul_f32_e32 v64, v64, v158
	v_mul_f32_e32 v65, v65, v158
	v_mul_f32_e32 v82, v94, v158
	v_mul_f32_e32 v83, v95, v158
	v_cvt_pk_bf16_f32 v80, v80, v81
	v_cvt_pk_bf16_f32 v81, v82, v83
	ds_write_b64 v149, v[80:81] offset:176
	v_mul_f32_e32 v66, v66, v158
	v_mul_f32_e32 v67, v67, v158
	v_cvt_pk_bf16_f32 v64, v64, v65
	v_cvt_pk_bf16_f32 v65, v66, v67
	ds_write_b64 v149, v[64:65] offset:192
	v_mul_f32_e32 v64, v68, v158
	v_mul_f32_e32 v65, v69, v158
	v_mul_f32_e32 v66, v70, v158
	v_mul_f32_e32 v67, v71, v158
	v_cvt_pk_bf16_f32 v64, v64, v65
	v_cvt_pk_bf16_f32 v65, v66, v67
	ds_write_b64 v149, v[64:65] offset:208
	v_mul_f32_e32 v64, v72, v158
	v_mul_f32_e32 v65, v73, v158
	v_mul_f32_e32 v66, v74, v158
	v_mul_f32_e32 v67, v75, v158
	v_cvt_pk_bf16_f32 v64, v64, v65
	v_cvt_pk_bf16_f32 v65, v66, v67
	ds_write_b64 v149, v[64:65] offset:224
	v_mul_f32_e32 v64, v76, v158
	v_mul_f32_e32 v65, v77, v158
	v_mul_f32_e32 v66, v78, v158
	v_mul_f32_e32 v67, v79, v158
	v_cvt_pk_bf16_f32 v64, v64, v65
	v_cvt_pk_bf16_f32 v65, v66, v67
	ds_write_b64 v149, v[64:65] offset:240
	v_ashrrev_i32_e32 v149, 31, v148
	v_lshlrev_b64 v[64:65], 10, v[148:149]
	v_bfe_u32 v70, v152, 4, 2
	v_lshl_add_u64 v[68:69], s[24:25], 0, v[64:65]
	v_mul_u32_u24_e32 v64, 0x110, v70
	s_waitcnt lgkmcnt(0)
	v_add3_u32 v72, v153, v184, v64
	ds_read_b128 v[194:197], v72
	ds_read_b128 v[198:201], v72 offset:1088
	ds_read_b128 v[202:205], v72 offset:2176
	ds_read_b128 v[206:209], v72 offset:3264
	ds_read_b128 v[210:213], v72 offset:4352
	ds_read_b128 v[214:217], v72 offset:5440
	ds_read_b128 v[218:221], v72 offset:6528
	ds_read_b128 v[222:225], v72 offset:7616
	v_lshl_add_u64 v[68:69], v[68:69], 0, s[22:23]
	v_lshl_add_u64 v[68:69], v[68:69], 0, v[184:185]
	v_lshlrev_b32_e32 v184, 10, v70
	v_lshl_add_u64 v[70:71], v[68:69], 0, v[184:185]
	s_waitcnt lgkmcnt(0)
	global_store_dwordx4 v[70:71], v[194:197], off
	v_or_b32_e32 v70, 0x1000, v184
	v_mov_b32_e32 v71, v185
	v_lshl_add_u64 v[70:71], v[68:69], 0, v[70:71]
	v_mfma_f32_32x32x16_bf16 v[32:47], v[144:147], v[128:131], v[32:47]
	global_store_dwordx4 v[70:71], v[198:201], off
	v_or_b32_e32 v70, 0x2000, v184
	v_mov_b32_e32 v71, v185
	v_lshl_add_u64 v[70:71], v[68:69], 0, v[70:71]
	s_mul_i32 s22, s54, 0x180
	global_store_dwordx4 v[70:71], v[202:205], off
	v_or_b32_e32 v70, 0x3000, v184
	v_mov_b32_e32 v71, v185
	v_lshl_add_u64 v[70:71], v[68:69], 0, v[70:71]
	v_mfma_f32_32x32x16_bf16 v[48:63], v[140:143], v[128:131], v[48:63]
	global_store_dwordx4 v[70:71], v[206:209], off
	v_or_b32_e32 v70, 0x4000, v184
	v_mov_b32_e32 v71, v185
	v_lshl_add_u64 v[70:71], v[68:69], 0, v[70:71]
	v_mul_f32_e32 v75, v32, v158
	global_store_dwordx4 v[70:71], v[210:213], off
	v_or_b32_e32 v70, 0x5000, v184
	v_mov_b32_e32 v71, v185
	v_lshl_add_u64 v[70:71], v[68:69], 0, v[70:71]
	v_mul_f32_e32 v76, v33, v158
	global_store_dwordx4 v[70:71], v[214:217], off
	v_or_b32_e32 v70, 0x6000, v184
	v_mov_b32_e32 v71, v185
	v_lshl_add_u64 v[70:71], v[68:69], 0, v[70:71]
	v_or_b32_e32 v184, 0x7000, v184
	global_store_dwordx4 v[70:71], v[218:221], off
	v_lshl_add_u64 v[68:69], v[68:69], 0, v[184:185]
	v_lshlrev_b64 v[32:33], 8, v[150:151]
	v_lshl_add_u64 v[32:33], s[68:69], 0, v[32:33]
	v_lshlrev_b32_e32 v184, 4, v155
	global_store_dwordx4 v[68:69], v[222:225], off
	s_waitcnt lgkmcnt(0)
; DEV void epi_ukv(f32x16 (&acc)[1][8], const Params& P, int layer, int batch, int m0, int head, int wid, int r32, int hi, char* lds) {
;     ...
;   float s = 0.f;
; #pragma unroll
;   for (int ni = 0; ni < 4; ++ni)
; #pragma unroll
;     for (int r = 0; r < 16; ++r) { acc[0][ni][r] *= rc; s += acc[0][ni][r] * acc[0][ni][r]; }
;   float4 kr[2][4];
; #pragma unroll
;   for (int b = 0; b < 2; ++b)
; #pragma unroll
;     for (int r4 = 0; r4 < 4; ++r4) {
;       kr[b][r4] = *reinterpret_cast<const float4*>(WS{P.ws}.KR() + (long)t * 64 + b * 32 + r4 * 8 + hi * 4);
;       s += kr[b][r4].x * kr[b][r4].x + kr[b][r4].y * kr[b][r4].y + kr[b][r4].z * kr[b][r4].z + kr[b][r4].w * kr[b][r4].w;
;     }
;   s = swapsum(s);
;   const float inv = __builtin_amdgcn_rsqf(s * (1.f / 192.f) + EPS);
;   const float* g = WS{P.ws}.consts() + layer * 1024 + 512;
;   char* dst = slab + r32 * 400;
; #pragma unroll
;   for (int ni = 0; ni < 4; ++ni)
; #pragma unroll
;     for (int r4 = 0; r4 < 4; ++r4) {
;       const int c = ni * 32 + r4 * 8 + hi * 4;
;       const float4 gg = *reinterpret_cast<const float4*>(g + c);
	v_mul_f32_e32 v73, v56, v158
	v_mul_f32_e32 v74, v57, v158
	v_lshl_add_u64 v[56:57], v[32:33], 0, v[184:185]
	v_mul_f32_e32 v64, v48, v158
	v_mul_f32_e32 v65, v49, v158
	v_mul_f32_e32 v67, v50, v158
	v_mul_f32_e32 v68, v51, v158
	flat_load_dwordx4 v[48:51], v[56:57]
	v_mul_f32_e32 v83, v40, v158
	v_mul_f32_e32 v84, v41, v158
	v_mul_f32_e32 v85, v42, v158
	v_mul_f32_e32 v86, v43, v158
	flat_load_dwordx4 v[40:43], v[56:57] offset:32
	v_mul_f32_e32 v79, v36, v158
	v_mul_f32_e32 v80, v37, v158
	v_mul_f32_e32 v81, v38, v158
	v_mul_f32_e32 v82, v39, v158
	flat_load_dwordx4 v[36:39], v[56:57] offset:64
	v_mfma_f32_32x32x16_bf16 v[16:31], v[136:139], v[128:131], v[16:31]
	v_mul_f32_e32 v77, v34, v158
	v_mul_f32_e32 v78, v35, v158
	flat_load_dwordx4 v[32:35], v[56:57] offset:96
	v_mul_f32_e32 v69, v52, v158
	v_mul_f32_e32 v70, v53, v158
	v_mul_f32_e32 v71, v54, v158
	v_mul_f32_e32 v72, v55, v158
	v_mul_f32_e32 v87, v44, v158
	v_mul_f32_e32 v88, v45, v158
	v_mul_f32_e32 v89, v46, v158
	v_mul_f32_e32 v90, v47, v158
	flat_load_dwordx4 v[52:55], v[56:57] offset:128
	flat_load_dwordx4 v[44:47], v[56:57] offset:160
	v_mul_f32_e32 v91, v16, v158
	v_mul_f32_e32 v92, v17, v158
	v_mul_f32_e32 v93, v18, v158
	v_mul_f32_e32 v94, v19, v158
	v_mul_f32_e32 v95, v20, v158
	v_mul_f32_e32 v96, v21, v158
	v_mul_f32_e32 v97, v22, v158
	v_mul_f32_e32 v98, v23, v158
	flat_load_dwordx4 v[20:23], v[56:57] offset:192
	flat_load_dwordx4 v[16:19], v[56:57] offset:224
	v_mul_f32_e32 v66, v65, v65
	v_fmac_f32_e32 v66, v64, v64
	v_fmac_f32_e32 v66, v67, v67
	v_fmac_f32_e32 v66, v68, v68
	v_fmac_f32_e32 v66, v69, v69
	v_mfma_f32_32x32x16_bf16 v[0:15], v[132:135], v[128:131], v[0:15]
	v_fmac_f32_e32 v66, v70, v70
	v_fmac_f32_e32 v66, v71, v71
	v_fmac_f32_e32 v66, v72, v72
	v_fmac_f32_e32 v66, v73, v73
	v_fmac_f32_e32 v66, v74, v74
	v_mul_f32_e32 v58, v58, v158
	v_fmac_f32_e32 v66, v58, v58
	v_mul_f32_e32 v59, v59, v158
	v_fmac_f32_e32 v66, v59, v59
	v_mul_f32_e32 v60, v60, v158
	v_fmac_f32_e32 v66, v60, v60
	v_mul_f32_e32 v61, v61, v158
	v_mul_f32_e32 v101, v26, v158
	v_mul_f32_e32 v56, v27, v158
	v_lshl_add_u64 v[26:27], s[10:11], 0, v[184:185]
	v_fmac_f32_e32 v66, v61, v61
	v_mul_f32_e32 v62, v62, v158
	v_mul_f32_e32 v57, v0, v158
	v_mul_f32_e32 v102, v1, v158
	v_mul_f32_e32 v103, v2, v158
	v_mul_f32_e32 v104, v3, v158
	flat_load_dwordx4 v[0:3], v[26:27] offset:2048
	global_load_dwordx4 v[194:197], v[26:27], off offset:2080
	global_load_dwordx4 v[198:201], v[26:27], off offset:2112
	global_load_dwordx4 v[202:205], v[26:27], off offset:2144
	global_load_dwordx4 v[206:209], v[26:27], off offset:2176
	global_load_dwordx4 v[210:213], v[26:27], off offset:2208
	global_load_dwordx4 v[214:217], v[26:27], off offset:2240
	global_load_dwordx4 v[218:221], v[26:27], off offset:2272
	global_load_dwordx4 v[222:225], v[26:27], off offset:2304
	global_load_dwordx4 v[232:235], v[26:27], off offset:2336
	global_load_dwordx4 v[236:239], v[26:27], off offset:2368
	global_load_dwordx4 v[240:243], v[26:27], off offset:2400
	global_load_dwordx4 v[244:247], v[26:27], off offset:2432
	global_load_dwordx4 v[248:251], v[26:27], off offset:2464
	global_load_dwordx4 v[170:173], v[26:27], off offset:2496
	global_load_dwordx4 v[174:177], v[26:27], off offset:2528
	v_fmac_f32_e32 v66, v62, v62
	v_mul_f32_e32 v63, v63, v158
	v_fmac_f32_e32 v66, v63, v63
	v_fmac_f32_e32 v66, v75, v75
	v_fmac_f32_e32 v66, v76, v76
	v_fmac_f32_e32 v66, v77, v77
	v_fmac_f32_e32 v66, v78, v78
	v_fmac_f32_e32 v66, v79, v79
	v_fmac_f32_e32 v66, v80, v80
	v_fmac_f32_e32 v66, v81, v81
	v_fmac_f32_e32 v66, v82, v82
	v_fmac_f32_e32 v66, v83, v83
	v_fmac_f32_e32 v66, v84, v84
	v_fmac_f32_e32 v66, v85, v85
	v_fmac_f32_e32 v66, v86, v86
	v_fmac_f32_e32 v66, v87, v87
	v_fmac_f32_e32 v66, v88, v88
	v_fmac_f32_e32 v66, v89, v89
	v_fmac_f32_e32 v66, v90, v90
	v_fmac_f32_e32 v66, v91, v91
	v_fmac_f32_e32 v66, v92, v92
	v_fmac_f32_e32 v66, v93, v93
	v_fmac_f32_e32 v66, v94, v94
	v_fmac_f32_e32 v66, v95, v95
	v_fmac_f32_e32 v66, v96, v96
	v_fmac_f32_e32 v66, v97, v97
	v_fmac_f32_e32 v66, v98, v98
	v_mul_f32_e32 v99, v24, v158
	v_fmac_f32_e32 v66, v99, v99
	v_mul_f32_e32 v100, v25, v158
	v_fmac_f32_e32 v66, v100, v100
	v_fmac_f32_e32 v66, v101, v101
	v_fmac_f32_e32 v66, v56, v56
	v_mul_f32_e32 v28, v28, v158
	v_fmac_f32_e32 v66, v28, v28
	v_mul_f32_e32 v29, v29, v158
	v_fmac_f32_e32 v66, v29, v29
	v_mul_f32_e32 v30, v30, v158
	v_fmac_f32_e32 v66, v30, v30
	v_mul_f32_e32 v31, v31, v158
	v_fmac_f32_e32 v66, v31, v31
	v_fmac_f32_e32 v66, v57, v57
	v_fmac_f32_e32 v66, v102, v102
	v_fmac_f32_e32 v66, v103, v103
	v_fmac_f32_e32 v66, v104, v104
	v_mul_f32_e32 v105, v4, v158
	v_fmac_f32_e32 v66, v105, v105
	v_mul_f32_e32 v106, v5, v158
	v_fmac_f32_e32 v66, v106, v106
	v_mul_f32_e32 v107, v6, v158
	v_fmac_f32_e32 v66, v107, v107
	v_mul_f32_e32 v108, v7, v158
	v_fmac_f32_e32 v66, v108, v108
	v_mul_f32_e32 v8, v8, v158
	v_fmac_f32_e32 v66, v8, v8
	v_mul_f32_e32 v9, v9, v158
	v_fmac_f32_e32 v66, v9, v9
	v_mul_f32_e32 v10, v10, v158
	v_fmac_f32_e32 v66, v10, v10
	v_mul_f32_e32 v11, v11, v158
	v_fmac_f32_e32 v66, v11, v11
	v_mul_f32_e32 v12, v12, v158
	v_fmac_f32_e32 v66, v12, v12
	v_mul_f32_e32 v13, v13, v158
	s_waitcnt vmcnt(0) lgkmcnt(0)
; DEV void epi_ukv(f32x16 (&acc)[1][8], const Params& P, int layer, int batch, int m0, int head, int wid, int r32, int hi, char* lds) {
;     ...
;       s += kr[b][r4].x * kr[b][r4].x + kr[b][r4].y * kr[b][r4].y + kr[b][r4].z * kr[b][r4].z + kr[b][r4].w * kr[b][r4].w;
;     }
;   s = swapsum(s);
;   const float inv = __builtin_amdgcn_rsqf(s * (1.f / 192.f) + EPS);
;   const float* g = WS{P.ws}.consts() + layer * 1024 + 512;
;   char* dst = slab + r32 * 400;
; #pragma unroll
;   for (int ni = 0; ni < 4; ++ni)
; #pragma unroll
;     for (int r4 = 0; r4 < 4; ++r4) {
;       const int c = ni * 32 + r4 * 8 + hi * 4;
;       const float4 gg = *reinterpret_cast<const float4*>(g + c);
;       const f32x16& a = acc[0][ni];
;       st4lds(dst, c, a[r4 * 4] * inv * gg.x, a[r4 * 4 + 1] * inv * gg.y, a[r4 * 4 + 2] * inv * gg.z, a[r4 * 4 + 3] * inv * gg.w);
;     }
	v_mul_f32_e32 v4, v49, v49
	v_fmac_f32_e32 v66, v13, v13
	v_mul_f32_e32 v14, v14, v158
	v_fmac_f32_e32 v4, v48, v48
	v_mul_f32_e32 v5, v41, v41
	v_fmac_f32_e32 v66, v14, v14
	v_mul_f32_e32 v15, v15, v158
	v_fmac_f32_e32 v4, v50, v50
	v_fmac_f32_e32 v5, v40, v40
	v_fmac_f32_e32 v66, v15, v15
	v_fmac_f32_e32 v4, v51, v51
	v_fmac_f32_e32 v5, v42, v42
	v_add_f32_e32 v4, v66, v4
	v_fmac_f32_e32 v5, v43, v43
	v_add_f32_e32 v4, v4, v5
	v_mul_f32_e32 v5, v37, v37
	v_fmac_f32_e32 v5, v36, v36
	v_fmac_f32_e32 v5, v38, v38
	v_fmac_f32_e32 v5, v39, v39
	v_add_f32_e32 v4, v4, v5
	v_mul_f32_e32 v5, v33, v33
	v_fmac_f32_e32 v5, v32, v32
	v_fmac_f32_e32 v5, v34, v34
	v_fmac_f32_e32 v5, v35, v35
	v_mov_b32_e32 v6, v53
	v_mov_b32_e32 v7, v45
	v_add_f32_e32 v24, v4, v5
	v_mov_b32_e32 v4, v52
	v_mov_b32_e32 v5, v44
	v_pk_mul_f32 v[6:7], v[6:7], v[6:7]
	v_lshlrev_b32_e32 v184, 5, v155
	v_pk_fma_f32 v[4:5], v[4:5], v[4:5], v[6:7]
	v_mov_b32_e32 v6, v54
	v_mov_b32_e32 v7, v46
	v_pk_fma_f32 v[4:5], v[6:7], v[6:7], v[4:5]
	v_mov_b32_e32 v6, v55
	v_mov_b32_e32 v7, v47
	v_pk_fma_f32 v[4:5], v[6:7], v[6:7], v[4:5]
	v_mov_b32_e32 v6, v21
	v_add_f32_e32 v4, v24, v4
	v_mov_b32_e32 v7, v17
	v_add_f32_e32 v24, v4, v5
	v_mov_b32_e32 v4, v20
	v_mov_b32_e32 v5, v16
	v_pk_mul_f32 v[6:7], v[6:7], v[6:7]
	s_nop 0
	v_pk_fma_f32 v[4:5], v[4:5], v[4:5], v[6:7]
	v_mov_b32_e32 v6, v22
	v_mov_b32_e32 v7, v18
	v_pk_fma_f32 v[4:5], v[6:7], v[6:7], v[4:5]
	v_mov_b32_e32 v6, v23
	v_mov_b32_e32 v7, v19
	v_pk_fma_f32 v[4:5], v[6:7], v[6:7], v[4:5]
	s_nop 0
	v_add_f32_e32 v4, v24, v4
	v_add_f32_e32 v4, v4, v5
	v_mov_b32_e32 v5, v4
	s_nop 1
	v_permlane32_swap_b32_e32 v4, v5
	v_add_f32_e32 v4, v4, v5
	v_fmamk_f32 v4, v4, 0x3baaaaab, v227
	v_rsq_f32_e32 v24, v4
	v_mul_u32_u24_e32 v4, 0x190, v154
	v_add3_u32 v25, v153, v4, v157
	v_mul_f32_e32 v5, v64, v24
	v_mul_f32_e32 v0, v0, v5
	v_mul_f32_e32 v5, v65, v24
	v_mul_f32_e32 v1, v1, v5
	v_mul_f32_e32 v5, v67, v24
	v_mul_f32_e32 v2, v2, v5
	v_mul_f32_e32 v5, v68, v24
	v_mul_f32_e32 v3, v3, v5
	v_cvt_pk_bf16_f32 v0, v0, v1
	v_cvt_pk_bf16_f32 v1, v2, v3
	ds_write_b64 v25, v[0:1]
	v_mul_f32_e32 v4, v69, v24
	v_mul_f32_e32 v5, v74, v24
	v_mul_f32_e32 v6, v62, v24
	v_mul_f32_e32 v7, v63, v24
	v_mul_f32_e32 v0, v4, v194
	v_mul_f32_e32 v4, v70, v24
	v_mul_f32_e32 v1, v4, v195
	v_mul_f32_e32 v4, v71, v24
	v_mul_f32_e32 v2, v4, v196
	v_mul_f32_e32 v4, v72, v24
	v_mul_f32_e32 v3, v4, v197
	v_cvt_pk_bf16_f32 v0, v0, v1
	v_cvt_pk_bf16_f32 v1, v2, v3
	ds_write_b64 v25, v[0:1] offset:16
	v_mul_f32_e32 v4, v73, v24
	v_mul_f32_e32 v0, v4, v198
	v_mul_f32_e32 v4, v58, v24
	v_mul_f32_e32 v1, v5, v199
	v_mul_f32_e32 v2, v4, v200
	v_mul_f32_e32 v4, v59, v24
	v_mul_f32_e32 v3, v4, v201
	v_cvt_pk_bf16_f32 v0, v0, v1
	v_cvt_pk_bf16_f32 v1, v2, v3
	ds_write_b64 v25, v[0:1] offset:32
	v_mul_f32_e32 v4, v60, v24
	v_mul_f32_e32 v5, v61, v24
	v_mul_f32_e32 v0, v4, v202
	v_mul_f32_e32 v1, v5, v203
	v_mul_f32_e32 v2, v6, v204
	v_mul_f32_e32 v3, v7, v205
	v_cvt_pk_bf16_f32 v0, v0, v1
	v_cvt_pk_bf16_f32 v1, v2, v3
	ds_write_b64 v25, v[0:1] offset:48
	v_mul_f32_e32 v4, v75, v24
	v_mul_f32_e32 v5, v76, v24
	v_mul_f32_e32 v6, v77, v24
	v_mul_f32_e32 v7, v78, v24
	v_mul_f32_e32 v0, v4, v206
	v_mul_f32_e32 v1, v5, v207
	v_mul_f32_e32 v2, v6, v208
	v_mul_f32_e32 v3, v7, v209
	v_cvt_pk_bf16_f32 v0, v0, v1
	v_cvt_pk_bf16_f32 v1, v2, v3
	ds_write_b64 v25, v[0:1] offset:64
	v_mul_f32_e32 v4, v79, v24
	v_mul_f32_e32 v5, v80, v24
	v_mul_f32_e32 v6, v81, v24
	v_mul_f32_e32 v7, v82, v24
	v_mul_f32_e32 v0, v4, v210
	v_mul_f32_e32 v1, v5, v211
	v_mul_f32_e32 v2, v6, v212
	v_mul_f32_e32 v3, v7, v213
	v_cvt_pk_bf16_f32 v0, v0, v1
	v_cvt_pk_bf16_f32 v1, v2, v3
	ds_write_b64 v25, v[0:1] offset:80
	v_mul_f32_e32 v4, v83, v24
	v_mul_f32_e32 v5, v84, v24
	v_mul_f32_e32 v6, v85, v24
	v_mul_f32_e32 v7, v86, v24
	v_mul_f32_e32 v0, v4, v214
	v_mul_f32_e32 v1, v5, v215
	v_mul_f32_e32 v2, v6, v216
	v_mul_f32_e32 v3, v7, v217
	v_cvt_pk_bf16_f32 v0, v0, v1
	v_cvt_pk_bf16_f32 v1, v2, v3
	ds_write_b64 v25, v[0:1] offset:96
	v_mul_f32_e32 v4, v87, v24
	v_mul_f32_e32 v5, v88, v24
	v_mul_f32_e32 v6, v89, v24
	v_mul_f32_e32 v7, v90, v24
	v_mul_f32_e32 v0, v4, v218
	v_mul_f32_e32 v1, v5, v219
	v_mul_f32_e32 v2, v6, v220
	v_mul_f32_e32 v3, v7, v221
	v_cvt_pk_bf16_f32 v0, v0, v1
	v_cvt_pk_bf16_f32 v1, v2, v3
	ds_write_b64 v25, v[0:1] offset:112
	v_mul_f32_e32 v4, v91, v24
	v_mul_f32_e32 v5, v92, v24
	v_mul_f32_e32 v6, v93, v24
	v_mul_f32_e32 v7, v94, v24
	v_mul_f32_e32 v0, v4, v222
	v_mul_f32_e32 v1, v5, v223
	v_mul_f32_e32 v2, v6, v224
	v_mul_f32_e32 v3, v7, v225
	v_cvt_pk_bf16_f32 v0, v0, v1
	v_cvt_pk_bf16_f32 v1, v2, v3
	ds_write_b64 v25, v[0:1] offset:128
	v_mul_f32_e32 v4, v95, v24
	v_mul_f32_e32 v5, v96, v24
	v_mul_f32_e32 v6, v97, v24
	v_mul_f32_e32 v7, v98, v24
	v_mul_f32_e32 v0, v4, v232
	v_mul_f32_e32 v1, v5, v233
	v_mul_f32_e32 v2, v6, v234
	v_mul_f32_e32 v3, v7, v235
	v_cvt_pk_bf16_f32 v0, v0, v1
	v_cvt_pk_bf16_f32 v1, v2, v3
	ds_write_b64 v25, v[0:1] offset:144
	v_mul_f32_e32 v4, v99, v24
	v_mul_f32_e32 v5, v100, v24
	v_mul_f32_e32 v6, v101, v24
	v_mul_f32_e32 v7, v56, v24
	v_mul_f32_e32 v0, v4, v236
	v_mul_f32_e32 v1, v5, v237
	v_mul_f32_e32 v2, v6, v238
	v_mul_f32_e32 v3, v7, v239
	v_cvt_pk_bf16_f32 v0, v0, v1
	v_cvt_pk_bf16_f32 v1, v2, v3
	ds_write_b64 v25, v[0:1] offset:160
	v_mul_f32_e32 v4, v28, v24
	v_mul_f32_e32 v5, v29, v24
	v_mul_f32_e32 v6, v30, v24
	v_mul_f32_e32 v7, v31, v24
	v_mov_b32_e32 v30, v48
	v_mov_b32_e32 v31, v52
	v_mov_b32_e32 v52, v49
	v_mov_b32_e32 v48, v50
	v_mov_b32_e32 v49, v54
	v_mov_b32_e32 v54, v51
	v_pk_mul_f32 v[30:31], v[30:31], v[24:25] op_sel_hi:[1,0]
; DEV void epi_ukv(f32x16 (&acc)[1][8], const Params& P, int layer, int batch, int m0, int head, int wid, int r32, int hi, char* lds) {
;     ...
;   for (int ni = 0; ni < 4; ++ni)
; #pragma unroll
;     for (int r4 = 0; r4 < 4; ++r4) {
;       const int c = ni * 32 + r4 * 8 + hi * 4;
;       const float4 gg = *reinterpret_cast<const float4*>(g + c);
;       const f32x16& a = acc[0][ni];
;       st4lds(dst, c, a[r4 * 4] * inv * gg.x, a[r4 * 4 + 1] * inv * gg.y, a[r4 * 4 + 2] * inv * gg.z, a[r4 * 4 + 3] * inv * gg.w);
;     }
;   const int pos = batch ? t : (t & 4095);
;   const float2* rp = WS{P.ws}.rope() + (long)pos * 32;
; #pragma unroll
;   for (int r4 = 0; r4 < 4; ++r4) {
;     const int i = r4 * 8 + hi * 4;
;     const float4 g1 = *reinterpret_cast<const float4*>(g + 128 + i), g2 = *reinterpret_cast<const float4*>(g + 160 + i);
;     const float4 cs01 = *reinterpret_cast<const float4*>(rp + i), cs23 = *reinterpret_cast<const float4*>(rp + i + 2);
;     const float x1[4] = {kr[0][r4].x * inv * g1.x, kr[0][r4].y * inv * g1.y, kr[0][r4].z * inv * g1.z, kr[0][r4].w * inv * g1.w};
;     const float x2[4] = {kr[1][r4].x * inv * g2.x, kr[1][r4].y * inv * g2.y, kr[1][r4].z * inv * g2.z, kr[1][r4].w * inv * g2.w};
;     const float cc[4] = {cs01.x, cs01.z, cs23.x, cs23.z}, sn[4] = {cs01.y, cs01.w, cs23.y, cs23.w};
;     st4lds(dst, 128 + i, x1[0] * cc[0] - x2[0] * sn[0], x1[1] * cc[1] - x2[1] * sn[1], x1[2] * cc[2] - x2[2] * sn[2], x1[3] * cc[3] - x2[3] * sn[3]);
;     st4lds(dst, 160 + i, x1[0] * sn[0] + x2[0] * cc[0], x1[1] * sn[1] + x2[1] * cc[1], x1[2] * sn[2] + x2[2] * cc[2], x1[3] * sn[3] + x2[3] * cc[3]);
	v_pk_mul_f32 v[50:51], v[52:53], v[24:25] op_sel_hi:[1,0]
	v_pk_mul_f32 v[48:49], v[48:49], v[24:25] op_sel_hi:[1,0]
	v_pk_mul_f32 v[52:53], v[54:55], v[24:25] op_sel_hi:[1,0]
	v_mul_f32_e32 v0, v4, v240
	v_mul_f32_e32 v1, v5, v241
	v_mul_f32_e32 v2, v6, v242
	v_mul_f32_e32 v3, v7, v243
	v_cvt_pk_bf16_f32 v0, v0, v1
	v_cvt_pk_bf16_f32 v1, v2, v3
	ds_write_b64 v25, v[0:1] offset:176
	v_mul_f32_e32 v4, v57, v24
	v_mul_f32_e32 v5, v102, v24
	v_mul_f32_e32 v6, v103, v24
	v_mul_f32_e32 v7, v104, v24
	v_mul_f32_e32 v0, v4, v244
	v_mul_f32_e32 v1, v5, v245
	v_mul_f32_e32 v2, v6, v246
	v_mul_f32_e32 v3, v7, v247
	v_cvt_pk_bf16_f32 v0, v0, v1
	v_cvt_pk_bf16_f32 v1, v2, v3
	ds_write_b64 v25, v[0:1] offset:192
	v_mul_f32_e32 v4, v105, v24
	v_mul_f32_e32 v5, v106, v24
	v_mul_f32_e32 v6, v107, v24
	v_mul_f32_e32 v7, v108, v24
	v_mul_f32_e32 v0, v4, v248
	v_mul_f32_e32 v1, v5, v249
	v_mul_f32_e32 v2, v6, v250
	v_mul_f32_e32 v3, v7, v251
	v_cvt_pk_bf16_f32 v0, v0, v1
	v_cvt_pk_bf16_f32 v1, v2, v3
	ds_write_b64 v25, v[0:1] offset:208
	v_mul_f32_e32 v4, v8, v24
	v_mul_f32_e32 v5, v9, v24
	v_mul_f32_e32 v6, v10, v24
	v_mul_f32_e32 v7, v11, v24
	v_bitop3_b32 v8, v148, s2, v154 bitop3:0xc8
	v_cndmask_b32_e64 v8, v150, v8, s[26:27]
	v_ashrrev_i32_e32 v9, 31, v8
	v_lshlrev_b64 v[8:9], 8, v[8:9]
	v_lshl_add_u64 v[8:9], s[12:13], 0, v[8:9]
	v_lshl_add_u64 v[28:29], v[8:9], 0, v[184:185]
	v_mul_f32_e32 v0, v4, v170
	v_mul_f32_e32 v1, v5, v171
	v_mul_f32_e32 v2, v6, v172
	v_mul_f32_e32 v3, v7, v173
	v_cvt_pk_bf16_f32 v0, v0, v1
	v_cvt_pk_bf16_f32 v1, v2, v3
	ds_write_b64 v25, v[0:1] offset:224
	v_mul_f32_e32 v4, v12, v24
	v_mul_f32_e32 v5, v13, v24
	v_mul_f32_e32 v6, v14, v24
	v_mul_f32_e32 v7, v15, v24
	v_mul_f32_e32 v0, v4, v174
	v_mul_f32_e32 v1, v5, v175
	v_mul_f32_e32 v2, v6, v176
	v_mul_f32_e32 v3, v7, v177
	v_cvt_pk_bf16_f32 v0, v0, v1
	v_cvt_pk_bf16_f32 v1, v2, v3
	ds_write_b64 v25, v[0:1] offset:240
	flat_load_dwordx4 v[0:3], v[26:27] offset:2560
	flat_load_dwordx4 v[4:7], v[26:27] offset:2688
	flat_load_dwordx4 v[8:11], v[28:29]
	flat_load_dwordx4 v[12:15], v[28:29] offset:16
	s_waitcnt vmcnt(0) lgkmcnt(0)
	v_mov_b32_e32 v54, v0
	v_mov_b32_e32 v55, v4
	v_mov_b32_e32 v4, v1
	v_mov_b32_e32 v0, v2
	v_mov_b32_e32 v1, v6
	v_mov_b32_e32 v6, v3
	v_pk_mul_f32 v[2:3], v[30:31], v[54:55]
	v_pk_mul_f32 v[4:5], v[50:51], v[4:5]
	v_pk_mul_f32 v[0:1], v[48:49], v[0:1]
	v_pk_mul_f32 v[6:7], v[52:53], v[6:7]
	v_pk_mul_f32 v[30:31], v[2:3], v[8:9]
	v_pk_mul_f32 v[48:49], v[4:5], v[10:11]
	v_pk_mul_f32 v[50:51], v[0:1], v[12:13]
	v_pk_mul_f32 v[52:53], v[6:7], v[14:15]
	v_pk_mul_f32 v[2:3], v[2:3], v[8:9] op_sel:[1,0] op_sel_hi:[0,1]
	v_pk_mul_f32 v[4:5], v[4:5], v[10:11] op_sel:[1,0] op_sel_hi:[0,1]
	v_pk_mul_f32 v[0:1], v[0:1], v[12:13] op_sel:[1,0] op_sel_hi:[0,1]
	v_pk_mul_f32 v[6:7], v[6:7], v[14:15] op_sel:[1,0] op_sel_hi:[0,1]
	v_sub_f32_e32 v8, v30, v31
	v_sub_f32_e32 v9, v48, v49
	v_sub_f32_e32 v10, v50, v51
	v_sub_f32_e32 v11, v52, v53
	v_add_f32_e32 v2, v2, v3
	v_add_f32_e32 v3, v4, v5
	v_add_f32_e32 v4, v0, v1
	v_cvt_pk_bf16_f32 v0, v8, v9
	v_cvt_pk_bf16_f32 v1, v10, v11
	v_add_f32_e32 v5, v6, v7
	ds_write_b64 v25, v[0:1] offset:256
	v_cvt_pk_bf16_f32 v0, v2, v3
	v_cvt_pk_bf16_f32 v1, v4, v5
	ds_write_b64 v25, v[0:1] offset:320
	flat_load_dwordx4 v[0:3], v[26:27] offset:2592
	flat_load_dwordx4 v[4:7], v[26:27] offset:2720
	flat_load_dwordx4 v[8:11], v[28:29] offset:64
	flat_load_dwordx4 v[12:15], v[28:29] offset:80
	v_mov_b32_e32 v30, v40
	v_mov_b32_e32 v31, v44
	v_mov_b32_e32 v44, v41
	v_mov_b32_e32 v40, v42
	v_mov_b32_e32 v41, v46
	v_mov_b32_e32 v46, v43
	v_pk_mul_f32 v[30:31], v[30:31], v[24:25] op_sel_hi:[1,0]
	v_pk_mul_f32 v[42:43], v[44:45], v[24:25] op_sel_hi:[1,0]
	v_pk_mul_f32 v[40:41], v[40:41], v[24:25] op_sel_hi:[1,0]
	v_pk_mul_f32 v[44:45], v[46:47], v[24:25] op_sel_hi:[1,0]
	s_waitcnt vmcnt(0) lgkmcnt(0)
	v_mov_b32_e32 v46, v0
	v_mov_b32_e32 v47, v4
	v_mov_b32_e32 v4, v1
	v_mov_b32_e32 v0, v2
	v_mov_b32_e32 v1, v6
	v_mov_b32_e32 v6, v3
	v_pk_mul_f32 v[2:3], v[30:31], v[46:47]
	v_pk_mul_f32 v[4:5], v[42:43], v[4:5]
	v_pk_mul_f32 v[0:1], v[40:41], v[0:1]
	v_pk_mul_f32 v[6:7], v[44:45], v[6:7]
	v_pk_mul_f32 v[30:31], v[2:3], v[8:9]
	v_pk_mul_f32 v[40:41], v[4:5], v[10:11]
	v_pk_mul_f32 v[42:43], v[0:1], v[12:13]
	v_pk_mul_f32 v[44:45], v[6:7], v[14:15]
	v_pk_mul_f32 v[2:3], v[2:3], v[8:9] op_sel:[1,0] op_sel_hi:[0,1]
	v_pk_mul_f32 v[4:5], v[4:5], v[10:11] op_sel:[1,0] op_sel_hi:[0,1]
	v_pk_mul_f32 v[0:1], v[0:1], v[12:13] op_sel:[1,0] op_sel_hi:[0,1]
	v_pk_mul_f32 v[6:7], v[6:7], v[14:15] op_sel:[1,0] op_sel_hi:[0,1]
	v_sub_f32_e32 v8, v30, v31
	v_sub_f32_e32 v9, v40, v41
	v_sub_f32_e32 v10, v42, v43
	v_sub_f32_e32 v11, v44, v45
	v_add_f32_e32 v2, v2, v3
	v_add_f32_e32 v3, v4, v5
	v_add_f32_e32 v4, v0, v1
	v_cvt_pk_bf16_f32 v0, v8, v9
	v_cvt_pk_bf16_f32 v1, v10, v11
	v_add_f32_e32 v5, v6, v7
	ds_write_b64 v25, v[0:1] offset:272
	v_cvt_pk_bf16_f32 v0, v2, v3
	v_cvt_pk_bf16_f32 v1, v4, v5
	ds_write_b64 v25, v[0:1] offset:336
	flat_load_dwordx4 v[8:11], v[26:27] offset:2624
	flat_load_dwordx4 v[4:7], v[26:27] offset:2752
	flat_load_dwordx4 v[0:3], v[28:29] offset:128
	flat_load_dwordx4 v[12:15], v[28:29] offset:144
	v_and_b32_e32 v40, 63, v152
	v_mul_lo_u16_e32 v41, 43, v40
	v_or_b32_e32 v42, 64, v40
	v_or_b32_e32 v43, 0x80, v40
	v_lshrrev_b16_e32 v41, 10, v41
	v_mul_lo_u16_e32 v53, 43, v42
	v_mul_lo_u16_e32 v54, 0xab, v43
	v_or_b32_e32 v44, 0xc0, v40
	v_or_b32_e32 v45, 0x100, v40
	v_or_b32_e32 v46, 0x180, v40
	v_or_b32_e32 v47, 0x140, v40
	v_or_b32_e32 v48, 0x200, v40
	v_or_b32_e32 v49, 0x1c0, v40
	v_or_b32_e32 v50, 0x280, v40
	v_or_b32_e32 v51, 0x240, v40
; DEV void epi_ukv(f32x16 (&acc)[1][8], const Params& P, int layer, int batch, int m0, int head, int wid, int r32, int hi, char* lds) {
;     ...
;   const int pos = batch ? t : (t & 4095);
;   const float2* rp = WS{P.ws}.rope() + (long)pos * 32;
; #pragma unroll
;   for (int r4 = 0; r4 < 4; ++r4) {
;     const int i = r4 * 8 + hi * 4;
;     const float4 g1 = *reinterpret_cast<const float4*>(g + 128 + i), g2 = *reinterpret_cast<const float4*>(g + 160 + i);
;     const float4 cs01 = *reinterpret_cast<const float4*>(rp + i), cs23 = *reinterpret_cast<const float4*>(rp + i + 2);
;     const float x1[4] = {kr[0][r4].x * inv * g1.x, kr[0][r4].y * inv * g1.y, kr[0][r4].z * inv * g1.z, kr[0][r4].w * inv * g1.w};
;     const float x2[4] = {kr[1][r4].x * inv * g2.x, kr[1][r4].y * inv * g2.y, kr[1][r4].z * inv * g2.z, kr[1][r4].w * inv * g2.w};
;     const float cc[4] = {cs01.x, cs01.z, cs23.x, cs23.z}, sn[4] = {cs01.y, cs01.w, cs23.y, cs23.w};
;     st4lds(dst, 128 + i, x1[0] * cc[0] - x2[0] * sn[0], x1[1] * cc[1] - x2[1] * sn[1], x1[2] * cc[2] - x2[2] * sn[2], x1[3] * cc[3] - x2[3] * sn[3]);
;     st4lds(dst, 160 + i, x1[0] * sn[0] + x2[0] * cc[0], x1[1] * sn[1] + x2[1] * cc[1], x1[2] * sn[2] + x2[2] * cc[2], x1[3] * sn[3] + x2[3] * cc[3]);
	v_or_b32_e32 v52, 0x2c0, v40
	v_mad_i32_i24 v40, v41, s58, v40
	v_mul_u32_u24_e32 v64, 0x190, v41
	v_mul_u32_u24_e32 v65, 0x300, v41
	v_lshrrev_b16_e32 v41, 10, v53
	v_lshrrev_b16_e32 v53, 12, v54
	v_mad_i32_i24 v69, v41, s58, v42
	v_mad_i32_i24 v72, v53, s58, v43
	v_mov_b32_e32 v42, v36
	v_mov_b32_e32 v43, v20
	v_mov_b32_e32 v20, v37
	v_mov_b32_e32 v36, v38
	v_mov_b32_e32 v37, v22
	v_mov_b32_e32 v22, v39
	v_pk_mul_f32 v[38:39], v[42:43], v[24:25] op_sel_hi:[1,0]
	v_pk_mul_f32 v[20:21], v[20:21], v[24:25] op_sel_hi:[1,0]
	v_pk_mul_f32 v[36:37], v[36:37], v[24:25] op_sel_hi:[1,0]
	v_pk_mul_f32 v[22:23], v[22:23], v[24:25] op_sel_hi:[1,0]
	v_mul_lo_u16_e32 v55, 0xab, v44
	v_mul_u32_u24_e32 v56, 0xaab, v45
	v_mul_u32_u24_e32 v57, 0xaab, v47
	v_mul_u32_u24_e32 v58, 0xaab, v46
	v_mul_u32_u24_e32 v59, 0xaab, v49
	v_mul_u32_u24_e32 v60, 0xaab, v48
	v_mul_u32_u24_e32 v61, 0xaab, v51
	v_mul_u32_u24_e32 v62, 0xaab, v50
	v_mov_b64_e32 v[30:31], s[70:71]
	v_mul_u32_u24_e32 v63, 0xaab, v52
	v_lshrrev_b16_e32 v54, 12, v55
	v_lshrrev_b32_e32 v55, 16, v56
	v_lshrrev_b32_e32 v56, 16, v57
	v_lshrrev_b32_e32 v66, 16, v58
	v_perm_b32 v57, v58, v57, s44
	v_lshrrev_b32_e32 v58, 16, v59
	v_lshrrev_b32_e32 v67, 16, v60
	v_perm_b32 v59, v60, v59, s44
	v_lshrrev_b32_e32 v60, 16, v61
	v_lshrrev_b32_e32 v68, 16, v62
	v_mad_i64_i32 v[30:31], s[2:3], v148, s39, v[30:31]
	v_perm_b32 v61, v62, v61, s44
	v_lshrrev_b32_e32 v62, 16, v63
	v_lshlrev_b32_e32 v63, 4, v40
	v_mad_i32_i24 v48, v67, s58, v48
	v_mad_i32_i24 v51, v60, s58, v51
	v_mad_i32_i24 v50, v68, s58, v50
	v_mad_i32_i24 v52, v62, s58, v52
	v_lshlrev_b32_e32 v75, 4, v48
	v_lshlrev_b32_e32 v77, 4, v51
	v_lshlrev_b32_e32 v78, 4, v50
	v_lshlrev_b32_e32 v40, 3, v40
	v_lshlrev_b32_e32 v184, 1, v65
	v_mul_u32_u24_e32 v70, 0x190, v41
	v_mul_u32_u24_e32 v71, 0x300, v41
	v_ashrrev_i32_e32 v41, 31, v40
	v_lshlrev_b32_e32 v79, 4, v52
	s_waitcnt vmcnt(0) lgkmcnt(0)
	v_mov_b32_e32 v42, v8
	v_mov_b32_e32 v43, v4
	v_mov_b32_e32 v4, v9
	v_mov_b32_e32 v8, v10
	v_mov_b32_e32 v9, v6
	v_mov_b32_e32 v6, v11
	v_pk_mul_f32 v[10:11], v[38:39], v[42:43]
	v_pk_mul_f32 v[4:5], v[20:21], v[4:5]
	v_pk_mul_f32 v[8:9], v[36:37], v[8:9]
	v_pk_mul_f32 v[6:7], v[22:23], v[6:7]
	v_pk_mul_f32 v[20:21], v[10:11], v[0:1]
	v_pk_mul_f32 v[22:23], v[4:5], v[2:3]
	v_pk_mul_f32 v[36:37], v[8:9], v[12:13]
	v_pk_mul_f32 v[38:39], v[6:7], v[14:15]
	v_pk_mul_f32 v[0:1], v[10:11], v[0:1] op_sel:[1,0] op_sel_hi:[0,1]
	v_pk_mul_f32 v[2:3], v[4:5], v[2:3] op_sel:[1,0] op_sel_hi:[0,1]
	v_pk_mul_f32 v[4:5], v[8:9], v[12:13] op_sel:[1,0] op_sel_hi:[0,1]
	v_pk_mul_f32 v[6:7], v[6:7], v[14:15] op_sel:[1,0] op_sel_hi:[0,1]
	v_sub_f32_e32 v8, v20, v21
	v_sub_f32_e32 v9, v22, v23
	v_sub_f32_e32 v10, v36, v37
	v_sub_f32_e32 v11, v38, v39
	v_add_f32_e32 v12, v0, v1
	v_cvt_pk_bf16_f32 v0, v8, v9
	v_cvt_pk_bf16_f32 v1, v10, v11
	v_add_f32_e32 v2, v2, v3
	v_add_f32_e32 v3, v4, v5
	v_add_f32_e32 v4, v6, v7
	ds_write_b64 v25, v[0:1] offset:288
	v_cvt_pk_bf16_f32 v0, v12, v2
	v_cvt_pk_bf16_f32 v1, v3, v4
	ds_write_b64 v25, v[0:1] offset:352
	flat_load_dwordx4 v[0:3], v[26:27] offset:2656
	flat_load_dwordx4 v[4:7], v[26:27] offset:2784
	flat_load_dwordx4 v[8:11], v[28:29] offset:192
	flat_load_dwordx4 v[12:15], v[28:29] offset:208
	v_mad_i32_i24 v23, v54, s58, v44
	v_mad_i32_i24 v36, v55, s58, v45
	v_mad_i32_i24 v38, v56, s58, v47
	v_mad_i32_i24 v42, v66, s58, v46
	v_mad_i32_i24 v44, v58, s58, v49
	v_pk_mul_lo_u16 v46, v59, s37 op_sel_hi:[1,0]
	v_mul_u32_u24_e32 v39, 0x190, v55
	v_mul_u32_u24_e32 v45, 0x300, v55
	v_pk_mul_lo_u16 v29, v57, s37 op_sel_hi:[1,0]
	v_mul_u32_u24_e32 v47, 0x300, v56
	v_mul_u32_u24_e32 v55, 0x300, v67
	v_pk_mul_lo_u16 v56, v61, s37 op_sel_hi:[1,0]
	v_mul_u32_u24_e32 v57, 0x300, v60
	v_mul_u32_u24_e32 v59, 0x190, v62
	v_mul_u32_u24_e32 v60, 0x300, v62
	v_lshl_add_u64 v[20:21], v[30:31], 0, s[22:23]
	v_add3_u32 v61, v153, v64, v63
	v_lshlrev_b32_e32 v31, 4, v69
	v_lshlrev_b32_e32 v22, 3, v69
	v_lshlrev_b32_e32 v62, 4, v72
	v_lshlrev_b32_e32 v26, 3, v72
	v_lshlrev_b32_e32 v64, 4, v36
	v_lshlrev_b32_e32 v30, 3, v36
	v_lshlrev_b32_e32 v67, 4, v38
	v_lshlrev_b32_e32 v36, 3, v38
	v_lshlrev_b32_e32 v69, 4, v42
	v_lshlrev_b32_e32 v38, 3, v42
	v_and_b32_e32 v72, 0xfff0, v46
	v_lshlrev_b32_e32 v73, 4, v44
	v_lshlrev_b32_e32 v42, 3, v44
	v_lshrrev_b32_e32 v74, 16, v46
	v_lshlrev_b32_e32 v44, 3, v48
	v_lshlrev_b32_e32 v46, 3, v51
	v_lshlrev_b32_e32 v48, 3, v50
	v_mov_b32_e32 v50, v32
	v_mov_b32_e32 v51, v16
	v_mov_b32_e32 v16, v33
	v_mov_b32_e32 v32, v34
	v_mov_b32_e32 v33, v18
	v_mov_b32_e32 v18, v35
	v_pk_mul_f32 v[34:35], v[50:51], v[24:25] op_sel_hi:[1,0]
	v_pk_mul_f32 v[16:17], v[16:17], v[24:25] op_sel_hi:[1,0]
	v_pk_mul_f32 v[32:33], v[32:33], v[24:25] op_sel_hi:[1,0]
	v_pk_mul_f32 v[18:19], v[18:19], v[24:25] op_sel_hi:[1,0]
	v_add3_u32 v70, v153, v70, v31
	v_lshlrev_b32_e32 v63, 4, v23
	v_lshlrev_b32_e32 v28, 3, v23
	v_ashrrev_i32_e32 v23, 31, v22
	v_mul_u32_u24_e32 v27, 0x190, v53
	v_add3_u32 v62, v153, v27, v62
	v_mul_u32_u24_e32 v43, 0x300, v53
	v_ashrrev_i32_e32 v27, 31, v26
	v_mul_u32_u24_e32 v37, 0x190, v54
	v_add3_u32 v63, v153, v37, v63
	v_mul_u32_u24_e32 v53, 0x300, v54
	v_mul_u32_u24_e32 v54, 0x300, v66
	v_mul_u32_u24_e32 v49, 0x300, v58
	v_mul_u32_u24_e32 v58, 0x300, v68
	v_and_b32_e32 v66, 0xfff0, v29
	v_lshrrev_b32_e32 v68, 16, v29
	v_ashrrev_i32_e32 v29, 31, v28
	v_add3_u32 v64, v153, v39, v64
	v_ashrrev_i32_e32 v31, 31, v30
	v_add3_u32 v66, v153, v66, v67
	v_ashrrev_i32_e32 v37, 31, v36
	v_ashrrev_i32_e32 v39, 31, v38
	v_and_b32_e32 v76, 0xfff0, v56
	v_lshrrev_b32_e32 v56, 16, v56
	s_waitcnt vmcnt(0) lgkmcnt(0)
; #define LDSP(T) __attribute__((address_space(3))) T*
; template <int NCH, int STRIDE> DEV void slab_flush(char* slab, u16* grow0, int gstride, int lane) {
;   asm volatile("s_waitcnt lgkmcnt(0)" ::: "memory");
; #pragma unroll
;   for (int i = 0; i < NCH / 2; ++i) {
;     const int q = i * 64 + lane, row = q / NCH, cc = q - row * NCH;
;     const u32x4 v = *(LDSP(const u32x4))(slab + row * STRIDE + cc * 16);
;     *reinterpret_cast<u32x4*>(grow0 + (long)row * gstride + cc * 8) = v;
;   }
;   asm volatile("s_waitcnt lgkmcnt(0)" ::: "memory");
; }
; DEV void epi_ukv(f32x16 (&acc)[1][8], const Params& P, int layer, int batch, int m0, int head, int wid, int r32, int hi, char* lds) {
;     ...
;     st4lds(dst, 128 + i, x1[0] * cc[0] - x2[0] * sn[0], x1[1] * cc[1] - x2[1] * sn[1], x1[2] * cc[2] - x2[2] * sn[2], x1[3] * cc[3] - x2[3] * sn[3]);
;     st4lds(dst, 160 + i, x1[0] * sn[0] + x2[0] * cc[0], x1[1] * sn[1] + x2[1] * cc[1], x1[2] * sn[2] + x2[2] * cc[2], x1[3] * sn[3] + x2[3] * cc[3]);
;   }
;   slab_flush<24, 400>(slab, WS{P.ws}.KB() + (long)(m0 + wid * 32) * 768 + head * 192, 768, hi * 32 + r32);
	v_mov_b32_e32 v50, v0
	v_mov_b32_e32 v51, v4
	v_mov_b32_e32 v4, v1
	v_mov_b32_e32 v0, v2
	v_mov_b32_e32 v1, v6
	v_mov_b32_e32 v6, v3
	v_pk_mul_f32 v[2:3], v[34:35], v[50:51]
	v_pk_mul_f32 v[4:5], v[16:17], v[4:5]
	v_pk_mul_f32 v[0:1], v[32:33], v[0:1]
	v_pk_mul_f32 v[6:7], v[18:19], v[6:7]
	v_pk_mul_f32 v[16:17], v[2:3], v[8:9]
	v_pk_mul_f32 v[18:19], v[4:5], v[10:11]
	v_pk_mul_f32 v[32:33], v[0:1], v[12:13]
	v_pk_mul_f32 v[34:35], v[6:7], v[14:15]
	v_pk_mul_f32 v[2:3], v[2:3], v[8:9] op_sel:[1,0] op_sel_hi:[0,1]
	v_pk_mul_f32 v[4:5], v[4:5], v[10:11] op_sel:[1,0] op_sel_hi:[0,1]
	v_pk_mul_f32 v[0:1], v[0:1], v[12:13] op_sel:[1,0] op_sel_hi:[0,1]
	v_pk_mul_f32 v[6:7], v[6:7], v[14:15] op_sel:[1,0] op_sel_hi:[0,1]
	v_sub_f32_e32 v8, v16, v17
	v_sub_f32_e32 v9, v18, v19
	v_sub_f32_e32 v10, v32, v33
	v_sub_f32_e32 v11, v34, v35
	v_add_f32_e32 v2, v2, v3
	v_add_f32_e32 v3, v4, v5
	v_add_f32_e32 v4, v0, v1
	v_cvt_pk_bf16_f32 v0, v8, v9
	v_cvt_pk_bf16_f32 v1, v10, v11
	v_add_f32_e32 v5, v6, v7
	ds_write_b64 v25, v[0:1] offset:304
	v_cvt_pk_bf16_f32 v0, v2, v3
	v_cvt_pk_bf16_f32 v1, v4, v5
	ds_write_b64 v25, v[0:1] offset:368
	s_waitcnt lgkmcnt(0)
	ds_read_b128 v[0:3], v61
	v_lshl_add_u64 v[4:5], v[20:21], 0, v[184:185]
	v_lshl_add_u64 v[4:5], v[40:41], 1, v[4:5]
	v_lshlrev_b32_e32 v184, 1, v71
	v_add3_u32 v6, v153, v68, v69
	s_waitcnt lgkmcnt(0)
	flat_store_dwordx4 v[4:5], v[0:3]
	ds_read_b128 v[0:3], v70
	v_lshl_add_u64 v[4:5], v[20:21], 0, v[184:185]
	v_lshl_add_u64 v[4:5], v[22:23], 1, v[4:5]
	v_lshlrev_b32_e32 v184, 1, v43
	v_add3_u32 v7, v153, v72, v73
	s_waitcnt lgkmcnt(0)
	flat_store_dwordx4 v[4:5], v[0:3]
	ds_read_b128 v[0:3], v62
	v_lshl_add_u64 v[4:5], v[20:21], 0, v[184:185]
	v_lshl_add_u64 v[4:5], v[26:27], 1, v[4:5]
	v_lshlrev_b32_e32 v184, 1, v53
	v_ashrrev_i32_e32 v43, 31, v42
	s_waitcnt lgkmcnt(0)
	flat_store_dwordx4 v[4:5], v[0:3]
	ds_read_b128 v[0:3], v63
	v_lshl_add_u64 v[4:5], v[20:21], 0, v[184:185]
	v_lshl_add_u64 v[4:5], v[28:29], 1, v[4:5]
	v_lshlrev_b32_e32 v184, 1, v45
	v_add3_u32 v8, v153, v74, v75
	s_waitcnt lgkmcnt(0)
	flat_store_dwordx4 v[4:5], v[0:3]
	ds_read_b128 v[0:3], v64
	v_lshl_add_u64 v[4:5], v[20:21], 0, v[184:185]
	v_lshl_add_u64 v[4:5], v[30:31], 1, v[4:5]
	v_lshlrev_b32_e32 v184, 1, v47
	v_ashrrev_i32_e32 v45, 31, v44
	s_waitcnt lgkmcnt(0)
	flat_store_dwordx4 v[4:5], v[0:3]
	ds_read_b128 v[0:3], v66
	v_lshl_add_u64 v[4:5], v[20:21], 0, v[184:185]
	v_lshl_add_u64 v[4:5], v[36:37], 1, v[4:5]
	v_lshlrev_b32_e32 v184, 1, v54
	v_ashrrev_i32_e32 v47, 31, v46
	s_waitcnt lgkmcnt(0)
	flat_store_dwordx4 v[4:5], v[0:3]
	ds_read_b128 v[0:3], v6
	v_lshl_add_u64 v[4:5], v[20:21], 0, v[184:185]
	v_lshl_add_u64 v[4:5], v[38:39], 1, v[4:5]
	v_lshlrev_b32_e32 v184, 1, v49
	v_add3_u32 v6, v153, v76, v77
	s_waitcnt lgkmcnt(0)
	flat_store_dwordx4 v[4:5], v[0:3]
	ds_read_b128 v[0:3], v7
	v_lshl_add_u64 v[4:5], v[20:21], 0, v[184:185]
	v_lshl_add_u64 v[4:5], v[42:43], 1, v[4:5]
	v_lshlrev_b32_e32 v184, 1, v55
	v_add3_u32 v7, v153, v56, v78
	s_waitcnt lgkmcnt(0)
	flat_store_dwordx4 v[4:5], v[0:3]
	ds_read_b128 v[0:3], v8
	v_lshl_add_u64 v[4:5], v[20:21], 0, v[184:185]
	v_lshl_add_u64 v[4:5], v[44:45], 1, v[4:5]
	v_lshlrev_b32_e32 v184, 1, v57
	v_ashrrev_i32_e32 v49, 31, v48
	s_waitcnt lgkmcnt(0)
	flat_store_dwordx4 v[4:5], v[0:3]
	ds_read_b128 v[0:3], v6
	v_lshl_add_u64 v[4:5], v[20:21], 0, v[184:185]
	v_lshl_add_u64 v[4:5], v[46:47], 1, v[4:5]
	v_lshlrev_b32_e32 v184, 1, v58
	v_add3_u32 v6, v153, v59, v79
	s_waitcnt lgkmcnt(0)
	flat_store_dwordx4 v[4:5], v[0:3]
	ds_read_b128 v[0:3], v7
	v_lshl_add_u64 v[4:5], v[20:21], 0, v[184:185]
	v_lshl_add_u64 v[4:5], v[48:49], 1, v[4:5]
	v_lshlrev_b32_e32 v184, 1, v60
	s_waitcnt lgkmcnt(0)
	flat_store_dwordx4 v[4:5], v[0:3]
	ds_read_b128 v[0:3], v6
	v_lshlrev_b32_e32 v6, 3, v52
	v_lshl_add_u64 v[4:5], v[20:21], 0, v[184:185]
	v_ashrrev_i32_e32 v7, 31, v6
	v_lshl_add_u64 v[4:5], v[6:7], 1, v[4:5]
	s_waitcnt lgkmcnt(0)
	flat_store_dwordx4 v[4:5], v[0:3]
	s_waitcnt lgkmcnt(0)
	s_waitcnt lgkmcnt(0)
	s_barrier
	s_branch .LBB0_355
